# speedup vs baseline: 1.0106x; 1.0039x over previous
; #define PG8_STAGE(bufoff, gbase, voff) do { _Pragma("unroll") for (int _i = 0; _i < 2; ++_i) \
;         __builtin_amdgcn_global_load_lds((const unsigned*)((const char*)(gbase) + (voff)[_i]), (PG8_LAS unsigned*)(lds + (bufoff) + ldsw + _i * 8192), 16, 0, 0); } while (0)
; #define PG8_LDA(dst, b, h) do { _Pragma("unroll") for (int m = 0; m < 4; ++m) _Pragma("unroll") for (int k = 0; k < 2; ++k) dst[m][k] = *(const PG8_LAS bf16x8*)(lds + PG8_SA(b, h) + aoff + m * 2048 + k * 1024); } while (0)
; #define PG8_MMA(ai, bj, At, Bt) do { __builtin_amdgcn_s_setprio(1); _Pragma("unroll") for (int m = 0; m < 4; ++m) _Pragma("unroll") for (int n = 0; n < 2; ++n) _Pragma("unroll") for (int k = 0; k < 2; ++k) \
;         acc[ai][bj][m][n] = __builtin_amdgcn_mfma_f32_16x16x32_bf16(Bt[n][k], At[m][k], acc[ai][bj][m][n], 0, 0, 0); __builtin_amdgcn_s_setprio(0); } while (0)
; #define PG8_WAIT_V(n) asm volatile("s_waitcnt vmcnt(" #n ")" ::: "memory")
; #define PG8_WAIT_L(n) asm volatile("s_waitcnt lgkmcnt(" #n ")" ::: "memory")
; #define PG8_BAR __builtin_amdgcn_s_barrier()
; #define PG8_SCHED __builtin_amdgcn_sched_barrier(0)
; template <class Epi, class Sched, bool ALIGN_EPI = false, bool SP2 = false>
; __device__ __forceinline__ void gemm_phase(PG8_LAS unsigned char* lds, const Gemm g, const Sched& S, const Epi& E) {
;     ...
;             PG8_WAIT_V(8); PG8_WAIT_L(0); PG8_BAR; PG8_MMA(0, 0, At, B0); PG8_MMA(0, 1, At, B1); PG8_BAR; PG8_SCHED;
;             PG8_LDA(At, 0, 1); PG8_STAGE(PG8_SB(0, 0), b2, voffB); PG8_STAGE(PG8_SB(0, 1), b2 + hstep, voffB); PG8_STAGE(PG8_SA(0, 0), a2, voffA);
;             PG8_WAIT_V(8); PG8_WAIT_L(0); PG8_BAR; PG8_MMA(1, 0, At, B0); PG8_MMA(1, 1, At, B1); PG8_BAR; PG8_SCHED;
.Lpe_noe:
	s_waitcnt vmcnt(24)
	s_waitcnt lgkmcnt(0)
	s_barrier
	s_setprio 1
	v_mfma_f32_16x16x32_bf16 v[126:129], v[130:133], v[198:201], 0
	v_mfma_f32_16x16x32_bf16 v[122:125], v[138:141], v[198:201], 0
	v_mfma_f32_16x16x32_bf16 v[110:113], v[130:133], v[206:209], 0
	v_mfma_f32_16x16x32_bf16 v[106:109], v[138:141], v[206:209], 0
	v_mfma_f32_16x16x32_bf16 v[94:97], v[130:133], v[214:217], 0
	v_mfma_f32_16x16x32_bf16 v[90:93], v[138:141], v[214:217], 0
	v_mfma_f32_16x16x32_bf16 v[78:81], v[130:133], v[222:225], 0
	v_mfma_f32_16x16x32_bf16 v[74:77], v[138:141], v[222:225], 0
	v_mfma_f32_16x16x32_bf16 v[126:129], v[134:137], v[202:205], v[126:129]
	v_mfma_f32_16x16x32_bf16 v[122:125], v[142:145], v[202:205], v[122:125]
	v_mfma_f32_16x16x32_bf16 v[110:113], v[134:137], v[210:213], v[110:113]
	v_mfma_f32_16x16x32_bf16 v[106:109], v[142:145], v[210:213], v[106:109]
	v_mfma_f32_16x16x32_bf16 v[94:97], v[134:137], v[218:221], v[94:97]
	v_mfma_f32_16x16x32_bf16 v[90:93], v[142:145], v[218:221], v[90:93]
	v_mfma_f32_16x16x32_bf16 v[78:81], v[134:137], v[226:229], v[78:81]
	v_mfma_f32_16x16x32_bf16 v[74:77], v[142:145], v[226:229], v[74:77]
	s_setprio 0
	s_setprio 1
	v_mfma_f32_16x16x32_bf16 v[118:121], v[146:149], v[198:201], 0
	v_mfma_f32_16x16x32_bf16 v[114:117], v[190:193], v[198:201], 0
	v_mfma_f32_16x16x32_bf16 v[102:105], v[146:149], v[206:209], 0
	v_mfma_f32_16x16x32_bf16 v[98:101], v[190:193], v[206:209], 0
	v_mfma_f32_16x16x32_bf16 v[86:89], v[146:149], v[214:217], 0
	v_mfma_f32_16x16x32_bf16 v[82:85], v[190:193], v[214:217], 0
	v_mfma_f32_16x16x32_bf16 v[70:73], v[146:149], v[222:225], 0
	v_mfma_f32_16x16x32_bf16 v[66:69], v[190:193], v[222:225], 0
	v_mfma_f32_16x16x32_bf16 v[118:121], v[170:173], v[202:205], v[118:121]
	v_mfma_f32_16x16x32_bf16 v[114:117], v[194:197], v[202:205], v[114:117]
	v_mfma_f32_16x16x32_bf16 v[102:105], v[170:173], v[210:213], v[102:105]
	v_mfma_f32_16x16x32_bf16 v[98:101], v[194:197], v[210:213], v[98:101]
	v_mfma_f32_16x16x32_bf16 v[86:89], v[170:173], v[218:221], v[86:89]
	v_mfma_f32_16x16x32_bf16 v[82:85], v[194:197], v[218:221], v[82:85]
	v_mfma_f32_16x16x32_bf16 v[70:73], v[170:173], v[226:229], v[70:73]
	v_mfma_f32_16x16x32_bf16 v[66:69], v[194:197], v[226:229], v[66:69]
	s_setprio 0
	s_barrier
	s_add_i32 s94, s94, s16
	v_lshl_add_u64 v[150:151], s[12:13], 0, v[156:157]
	s_mov_b32 m0, s94
	ds_read_b128 v[198:201], v186 offset:16384
	ds_read_b128 v[202:205], v186 offset:17408
	ds_read_b128 v[206:209], v186 offset:18432
	ds_read_b128 v[210:213], v186 offset:19456
	ds_read_b128 v[214:217], v186 offset:20480
	ds_read_b128 v[218:221], v186 offset:21504
	ds_read_b128 v[222:225], v186 offset:22528
	ds_read_b128 v[226:229], v186 offset:23552
	global_load_lds_dwordx4 v[150:151], off
	s_add_i32 m0, s94, 0x2000
	s_add_u32 s94, s12, 0x40000
	v_lshl_add_u64 v[166:167], s[12:13], 0, v[160:161]
	s_addc_u32 s95, s13, 0
	s_add_i32 vcc_hi, vcc_hi, s16
	global_load_lds_dwordx4 v[166:167], off
	v_lshl_add_u64 v[230:231], s[94:95], 0, v[156:157]
	s_mov_b32 m0, vcc_hi
	v_lshl_add_u64 v[232:233], s[44:45], 0, v[158:159]
	global_load_lds_dwordx4 v[230:231], off
	v_lshl_add_u64 v[230:231], s[94:95], 0, v[160:161]
	s_add_i32 m0, vcc_hi, 0x2000
	s_nop 0
	global_load_lds_dwordx4 v[230:231], off
	v_lshl_add_u64 v[230:231], s[44:45], 0, v[154:155]
	s_mov_b32 m0, s17
	s_nop 0
	global_load_lds_dwordx4 v[230:231], off
	s_mov_b32 m0, s51
	s_nop 0
	global_load_lds_dwordx4 v[232:233], off
	s_cmp_eq_u32 s87, 1
	s_cbranch_scc1 .Lpe_w2_strict
	s_waitcnt vmcnt(24)
	s_branch .Lpe_w2_done

; #define PG8_STAGE(bufoff, gbase, voff) do { _Pragma("unroll") for (int _i = 0; _i < 2; ++_i) \
;         __builtin_amdgcn_global_load_lds((const unsigned*)((const char*)(gbase) + (voff)[_i]), (PG8_LAS unsigned*)(lds + (bufoff) + ldsw + _i * 8192), 16, 0, 0); } while (0)
; #define PG8_LDA(dst, b, h) do { _Pragma("unroll") for (int m = 0; m < 4; ++m) _Pragma("unroll") for (int k = 0; k < 2; ++k) dst[m][k] = *(const PG8_LAS bf16x8*)(lds + PG8_SA(b, h) + aoff + m * 2048 + k * 1024); } while (0)
; #define PG8_LDB(dst, b, h) do { _Pragma("unroll") for (int n = 0; n < 2; ++n) _Pragma("unroll") for (int k = 0; k < 2; ++k) dst[n][k] = *(const PG8_LAS bf16x8*)(lds + PG8_SB(b, h) + boff + n * 2048 + k * 1024); } while (0)
; #define PG8_MMA(ai, bj, At, Bt) do { __builtin_amdgcn_s_setprio(1); _Pragma("unroll") for (int m = 0; m < 4; ++m) _Pragma("unroll") for (int n = 0; n < 2; ++n) _Pragma("unroll") for (int k = 0; k < 2; ++k) \
;         acc[ai][bj][m][n] = __builtin_amdgcn_mfma_f32_16x16x32_bf16(Bt[n][k], At[m][k], acc[ai][bj][m][n], 0, 0, 0); __builtin_amdgcn_s_setprio(0); } while (0)
; #define PG8_WAIT_V(n) asm volatile("s_waitcnt vmcnt(" #n ")" ::: "memory")
; #define PG8_WAIT_L(n) asm volatile("s_waitcnt lgkmcnt(" #n ")" ::: "memory")
; #define PG8_BAR __builtin_amdgcn_s_barrier()
; #define PG8_SCHED __builtin_amdgcn_sched_barrier(0)
; template <class Epi, class Sched, bool ALIGN_EPI = false, bool SP2 = false>
; __device__ __forceinline__ void gemm_phase(PG8_LAS unsigned char* lds, const Gemm g, const Sched& S, const Epi& E) {
;     ...
;             PG8_WAIT_V(8); PG8_WAIT_L(0); PG8_BAR; PG8_MMA(1, 0, At, B0); PG8_MMA(1, 1, At, B1); PG8_BAR; PG8_SCHED;
;             PG8_LDB(B0, 1, 0); PG8_LDB(B1, 1, 1); PG8_SCHED; PG8_LDA(At, 1, 0); PG8_STAGE(PG8_SA(0, 1), a2 + hstepA, voffA);
;             PG8_WAIT_V(8); PG8_WAIT_L(0); PG8_BAR; PG8_MMA(0, 0, At, B0); PG8_MMA(0, 1, At, B1); PG8_BAR; PG8_SCHED;
;             PG8_LDA(At, 1, 1); PG8_STAGE(PG8_SB(1, 0), b3, voffB); PG8_STAGE(PG8_SB(1, 1), b3 + hstep, voffB); PG8_STAGE(PG8_SA(1, 0), a3, voffA);
.Lpe_w2_done:
	s_waitcnt lgkmcnt(0)
	s_barrier
	s_setprio 1
	v_mfma_f32_16x16x32_bf16 v[62:65], v[130:133], v[198:201], 0
	v_mfma_f32_16x16x32_bf16 v[58:61], v[138:141], v[198:201], 0
	v_mfma_f32_16x16x32_bf16 v[46:49], v[130:133], v[206:209], 0
	v_mfma_f32_16x16x32_bf16 v[42:45], v[138:141], v[206:209], 0
	v_mfma_f32_16x16x32_bf16 v[30:33], v[130:133], v[214:217], 0
	v_mfma_f32_16x16x32_bf16 v[26:29], v[138:141], v[214:217], 0
	v_mfma_f32_16x16x32_bf16 v[14:17], v[130:133], v[222:225], 0
	v_mfma_f32_16x16x32_bf16 v[10:13], v[138:141], v[222:225], 0
	v_mfma_f32_16x16x32_bf16 v[62:65], v[134:137], v[202:205], v[62:65]
	v_mfma_f32_16x16x32_bf16 v[58:61], v[142:145], v[202:205], v[58:61]
	v_mfma_f32_16x16x32_bf16 v[46:49], v[134:137], v[210:213], v[46:49]
	v_mfma_f32_16x16x32_bf16 v[42:45], v[142:145], v[210:213], v[42:45]
	v_mfma_f32_16x16x32_bf16 v[30:33], v[134:137], v[218:221], v[30:33]
	v_mfma_f32_16x16x32_bf16 v[26:29], v[142:145], v[218:221], v[26:29]
	v_mfma_f32_16x16x32_bf16 v[14:17], v[134:137], v[226:229], v[14:17]
	v_mfma_f32_16x16x32_bf16 v[10:13], v[142:145], v[226:229], v[10:13]
	s_setprio 0
	s_setprio 1
	v_mfma_f32_16x16x32_bf16 v[54:57], v[146:149], v[198:201], 0
	v_mfma_f32_16x16x32_bf16 v[50:53], v[190:193], v[198:201], 0
	v_mfma_f32_16x16x32_bf16 v[38:41], v[146:149], v[206:209], 0
	v_mfma_f32_16x16x32_bf16 v[34:37], v[190:193], v[206:209], 0
	v_mfma_f32_16x16x32_bf16 v[22:25], v[146:149], v[214:217], 0
	v_mfma_f32_16x16x32_bf16 v[18:21], v[190:193], v[214:217], 0
	v_mfma_f32_16x16x32_bf16 v[6:9], v[146:149], v[222:225], 0
	v_mfma_f32_16x16x32_bf16 v[2:5], v[190:193], v[222:225], 0
	v_mfma_f32_16x16x32_bf16 v[54:57], v[170:173], v[202:205], v[54:57]
	v_mfma_f32_16x16x32_bf16 v[50:53], v[194:197], v[202:205], v[50:53]
	v_mfma_f32_16x16x32_bf16 v[38:41], v[170:173], v[210:213], v[38:41]
	v_mfma_f32_16x16x32_bf16 v[34:37], v[194:197], v[210:213], v[34:37]
	v_mfma_f32_16x16x32_bf16 v[22:25], v[170:173], v[218:221], v[22:25]
	v_mfma_f32_16x16x32_bf16 v[18:21], v[194:197], v[218:221], v[18:21]
	v_mfma_f32_16x16x32_bf16 v[6:9], v[170:173], v[226:229], v[6:9]
	v_mfma_f32_16x16x32_bf16 v[2:5], v[194:197], v[226:229], v[2:5]
	s_setprio 0
	s_barrier
	s_add_i32 s94, 0, 0x18000
	v_add_u32_e32 v0, s94, v179
	s_add_i32 s95, 0, 0x1c000
	ds_read_b128 v[130:133], v0
	ds_read_b128 v[134:137], v0 offset:1024
	ds_read_b128 v[138:141], v0 offset:2048
	ds_read_b128 v[142:145], v0 offset:3072
	v_add_u32_e32 v0, s95, v179
	ds_read_b128 v[146:149], v0
	ds_read_b128 v[170:173], v0 offset:1024
	ds_read_b128 v[190:193], v0 offset:2048
	ds_read_b128 v[194:197], v0 offset:3072
	s_add_u32 s44, s44, 0x40000
	s_addc_u32 s45, s45, 0
	s_mov_b32 m0, s35
	v_lshl_add_u64 v[234:235], s[44:45], 0, v[154:155]
	ds_read_b128 v[198:201], v186 offset:32768
	ds_read_b128 v[202:205], v186 offset:33792
	ds_read_b128 v[206:209], v186 offset:34816
	ds_read_b128 v[210:213], v186 offset:35840
	ds_read_b128 v[214:217], v186 offset:36864
	ds_read_b128 v[218:221], v186 offset:37888
	ds_read_b128 v[222:225], v186 offset:38912
	ds_read_b128 v[226:229], v186 offset:39936
	global_load_lds_dwordx4 v[234:235], off
	v_lshl_add_u64 v[234:235], s[44:45], 0, v[158:159]
	s_mov_b32 m0, s30
	s_nop 0
	global_load_lds_dwordx4 v[234:235], off
	s_cmp_eq_u32 s87, 1
	s_cbranch_scc1 .Lpe_w3_strict
	s_waitcnt vmcnt(24)
	s_branch .Lpe_w3_done

; #define PG8_STAGE(bufoff, gbase, voff) do { _Pragma("unroll") for (int _i = 0; _i < 2; ++_i) \
;         __builtin_amdgcn_global_load_lds((const unsigned*)((const char*)(gbase) + (voff)[_i]), (PG8_LAS unsigned*)(lds + (bufoff) + ldsw + _i * 8192), 16, 0, 0); } while (0)
; #define PG8_LDA(dst, b, h) do { _Pragma("unroll") for (int m = 0; m < 4; ++m) _Pragma("unroll") for (int k = 0; k < 2; ++k) dst[m][k] = *(const PG8_LAS bf16x8*)(lds + PG8_SA(b, h) + aoff + m * 2048 + k * 1024); } while (0)
; #define PG8_MMA(ai, bj, At, Bt) do { __builtin_amdgcn_s_setprio(1); _Pragma("unroll") for (int m = 0; m < 4; ++m) _Pragma("unroll") for (int n = 0; n < 2; ++n) _Pragma("unroll") for (int k = 0; k < 2; ++k) \
;         acc[ai][bj][m][n] = __builtin_amdgcn_mfma_f32_16x16x32_bf16(Bt[n][k], At[m][k], acc[ai][bj][m][n], 0, 0, 0); __builtin_amdgcn_s_setprio(0); } while (0)
; #define PG8_WAIT_V(n) asm volatile("s_waitcnt vmcnt(" #n ")" ::: "memory")
; #define PG8_WAIT_L(n) asm volatile("s_waitcnt lgkmcnt(" #n ")" ::: "memory")
; #define PG8_BAR __builtin_amdgcn_s_barrier()
; #define PG8_SCHED __builtin_amdgcn_sched_barrier(0)
; template <class Epi, class Sched, bool ALIGN_EPI = false, bool SP2 = false>
; __device__ __forceinline__ void gemm_phase(PG8_LAS unsigned char* lds, const Gemm g, const Sched& S, const Epi& E) {
;     ...
;             PG8_WAIT_V(8); PG8_WAIT_L(0); PG8_BAR; PG8_MMA(0, 0, At, B0); PG8_MMA(0, 1, At, B1); PG8_BAR; PG8_SCHED;
;             PG8_LDA(At, 1, 1); PG8_STAGE(PG8_SB(1, 0), b3, voffB); PG8_STAGE(PG8_SB(1, 1), b3 + hstep, voffB); PG8_STAGE(PG8_SA(1, 0), a3, voffA);
;             PG8_WAIT_V(8); PG8_WAIT_L(0); PG8_BAR; PG8_MMA(1, 0, At, B0); PG8_MMA(1, 1, At, B1); PG8_BAR; PG8_SCHED;
.Lpe_w3_done:
	s_waitcnt lgkmcnt(0)
	s_barrier
	s_setprio 1
	v_mfma_f32_16x16x32_bf16 v[126:129], v[130:133], v[198:201], v[126:129]
	v_mfma_f32_16x16x32_bf16 v[122:125], v[138:141], v[198:201], v[122:125]
	v_mfma_f32_16x16x32_bf16 v[110:113], v[130:133], v[206:209], v[110:113]
	v_mfma_f32_16x16x32_bf16 v[106:109], v[138:141], v[206:209], v[106:109]
	v_mfma_f32_16x16x32_bf16 v[94:97], v[130:133], v[214:217], v[94:97]
	v_mfma_f32_16x16x32_bf16 v[90:93], v[138:141], v[214:217], v[90:93]
	v_mfma_f32_16x16x32_bf16 v[78:81], v[130:133], v[222:225], v[78:81]
	v_mfma_f32_16x16x32_bf16 v[74:77], v[138:141], v[222:225], v[74:77]
	v_mfma_f32_16x16x32_bf16 v[126:129], v[134:137], v[202:205], v[126:129]
	v_mfma_f32_16x16x32_bf16 v[122:125], v[142:145], v[202:205], v[122:125]
	v_mfma_f32_16x16x32_bf16 v[110:113], v[134:137], v[210:213], v[110:113]
	v_mfma_f32_16x16x32_bf16 v[106:109], v[142:145], v[210:213], v[106:109]
	v_mfma_f32_16x16x32_bf16 v[94:97], v[134:137], v[218:221], v[94:97]
	v_mfma_f32_16x16x32_bf16 v[90:93], v[142:145], v[218:221], v[90:93]
	v_mfma_f32_16x16x32_bf16 v[78:81], v[134:137], v[226:229], v[78:81]
	v_mfma_f32_16x16x32_bf16 v[74:77], v[142:145], v[226:229], v[74:77]
	s_setprio 0
	s_setprio 1
	v_mfma_f32_16x16x32_bf16 v[118:121], v[146:149], v[198:201], v[118:121]
	v_mfma_f32_16x16x32_bf16 v[114:117], v[190:193], v[198:201], v[114:117]
	v_mfma_f32_16x16x32_bf16 v[102:105], v[146:149], v[206:209], v[102:105]
	v_mfma_f32_16x16x32_bf16 v[98:101], v[190:193], v[206:209], v[98:101]
	v_mfma_f32_16x16x32_bf16 v[86:89], v[146:149], v[214:217], v[86:89]
	v_mfma_f32_16x16x32_bf16 v[82:85], v[190:193], v[214:217], v[82:85]
	v_mfma_f32_16x16x32_bf16 v[70:73], v[146:149], v[222:225], v[70:73]
	v_mfma_f32_16x16x32_bf16 v[66:69], v[190:193], v[222:225], v[66:69]
	v_mfma_f32_16x16x32_bf16 v[118:121], v[170:173], v[202:205], v[118:121]
	v_mfma_f32_16x16x32_bf16 v[114:117], v[194:197], v[202:205], v[114:117]
	v_mfma_f32_16x16x32_bf16 v[102:105], v[170:173], v[210:213], v[102:105]
	v_mfma_f32_16x16x32_bf16 v[98:101], v[194:197], v[210:213], v[98:101]
	v_mfma_f32_16x16x32_bf16 v[86:89], v[170:173], v[218:221], v[86:89]
	v_mfma_f32_16x16x32_bf16 v[82:85], v[194:197], v[218:221], v[82:85]
	v_mfma_f32_16x16x32_bf16 v[70:73], v[170:173], v[226:229], v[70:73]
	v_mfma_f32_16x16x32_bf16 v[66:69], v[194:197], v[226:229], v[66:69]
	s_setprio 0
	s_barrier
	s_add_i32 s44, s94, s16
	v_lshl_add_u64 v[150:151], v[150:151], 0, s[48:49]
	s_mov_b32 m0, s44
	ds_read_b128 v[198:201], v186 offset:49152
	ds_read_b128 v[202:205], v186 offset:50176
	ds_read_b128 v[206:209], v186 offset:51200
	ds_read_b128 v[210:213], v186 offset:52224
	ds_read_b128 v[214:217], v186 offset:53248
	ds_read_b128 v[218:221], v186 offset:54272
	ds_read_b128 v[222:225], v186 offset:55296
	ds_read_b128 v[226:229], v186 offset:56320
	global_load_lds_dwordx4 v[150:151], off
	s_add_i32 m0, s44, 0x2000
	s_add_u32 s12, s12, 0x40080
	v_lshl_add_u64 v[150:151], v[166:167], 0, s[48:49]
	s_addc_u32 s13, s13, 0
	s_add_i32 s44, s95, s16
	global_load_lds_dwordx4 v[150:151], off
	v_lshl_add_u64 v[150:151], s[12:13], 0, v[156:157]
	s_mov_b32 m0, s44
	s_nop 0
	global_load_lds_dwordx4 v[150:151], off
	v_lshl_add_u64 v[150:151], s[12:13], 0, v[160:161]
	s_add_i32 m0, s44, 0x2000
	s_nop 0
	global_load_lds_dwordx4 v[150:151], off
	v_lshl_add_u64 v[150:151], v[230:231], 0, s[48:49]
	s_mov_b32 m0, s59
	s_nop 0
	global_load_lds_dwordx4 v[150:151], off
	v_lshl_add_u64 v[150:151], v[232:233], 0, s[48:49]
	s_mov_b32 m0, s86
	s_nop 0
	global_load_lds_dwordx4 v[150:151], off
	s_waitcnt vmcnt(8)
	s_waitcnt lgkmcnt(0)
	s_barrier
	s_setprio 1
	v_mfma_f32_16x16x32_bf16 v[62:65], v[130:133], v[198:201], v[62:65]
	v_mfma_f32_16x16x32_bf16 v[58:61], v[138:141], v[198:201], v[58:61]
	v_mfma_f32_16x16x32_bf16 v[46:49], v[130:133], v[206:209], v[46:49]
	v_mfma_f32_16x16x32_bf16 v[42:45], v[138:141], v[206:209], v[42:45]
	v_mfma_f32_16x16x32_bf16 v[30:33], v[130:133], v[214:217], v[30:33]
	v_mfma_f32_16x16x32_bf16 v[26:29], v[138:141], v[214:217], v[26:29]
	v_mfma_f32_16x16x32_bf16 v[14:17], v[130:133], v[222:225], v[14:17]
	v_mfma_f32_16x16x32_bf16 v[10:13], v[138:141], v[222:225], v[10:13]
	v_mfma_f32_16x16x32_bf16 v[62:65], v[134:137], v[202:205], v[62:65]
	v_mfma_f32_16x16x32_bf16 v[58:61], v[142:145], v[202:205], v[58:61]
	v_mfma_f32_16x16x32_bf16 v[46:49], v[134:137], v[210:213], v[46:49]
	v_mfma_f32_16x16x32_bf16 v[42:45], v[142:145], v[210:213], v[42:45]
	v_mfma_f32_16x16x32_bf16 v[30:33], v[134:137], v[218:221], v[30:33]
	v_mfma_f32_16x16x32_bf16 v[26:29], v[142:145], v[218:221], v[26:29]
	v_mfma_f32_16x16x32_bf16 v[14:17], v[134:137], v[226:229], v[14:17]
	v_mfma_f32_16x16x32_bf16 v[10:13], v[142:145], v[226:229], v[10:13]
	s_setprio 0
	s_setprio 1
	v_mfma_f32_16x16x32_bf16 v[54:57], v[146:149], v[198:201], v[54:57]
	v_mfma_f32_16x16x32_bf16 v[50:53], v[190:193], v[198:201], v[50:53]
	v_mfma_f32_16x16x32_bf16 v[38:41], v[146:149], v[206:209], v[38:41]
	v_mfma_f32_16x16x32_bf16 v[34:37], v[190:193], v[206:209], v[34:37]
	v_mfma_f32_16x16x32_bf16 v[22:25], v[146:149], v[214:217], v[22:25]
	v_mfma_f32_16x16x32_bf16 v[18:21], v[190:193], v[214:217], v[18:21]
	v_mfma_f32_16x16x32_bf16 v[6:9], v[146:149], v[222:225], v[6:9]
	v_mfma_f32_16x16x32_bf16 v[2:5], v[190:193], v[222:225], v[2:5]
	v_mfma_f32_16x16x32_bf16 v[54:57], v[170:173], v[202:205], v[54:57]
	v_mfma_f32_16x16x32_bf16 v[50:53], v[194:197], v[202:205], v[50:53]
	v_mfma_f32_16x16x32_bf16 v[38:41], v[170:173], v[210:213], v[38:41]
	v_mfma_f32_16x16x32_bf16 v[34:37], v[194:197], v[210:213], v[34:37]
	v_mfma_f32_16x16x32_bf16 v[22:25], v[170:173], v[218:221], v[22:25]
	v_mfma_f32_16x16x32_bf16 v[18:21], v[194:197], v[218:221], v[18:21]
	v_mfma_f32_16x16x32_bf16 v[6:9], v[170:173], v[226:229], v[6:9]
	v_mfma_f32_16x16x32_bf16 v[2:5], v[194:197], v[226:229], v[2:5]
	s_setprio 0
	s_barrier
	s_add_i32 vcc_lo, vcc_lo, 2
	s_add_u32 s10, s10, 0x100
	s_addc_u32 s11, s11, 0
	s_add_u32 s47, s47, 0x100
	s_addc_u32 s63, s63, 0
; #define PG8_STAGE(bufoff, gbase, voff) do { _Pragma("unroll") for (int _i = 0; _i < 2; ++_i) \
;         __builtin_amdgcn_global_load_lds((const unsigned*)((const char*)(gbase) + (voff)[_i]), (PG8_LAS unsigned*)(lds + (bufoff) + ldsw + _i * 8192), 16, 0, 0); } while (0)
; #define PG8_LDA(dst, b, h) do { _Pragma("unroll") for (int m = 0; m < 4; ++m) _Pragma("unroll") for (int k = 0; k < 2; ++k) dst[m][k] = *(const PG8_LAS bf16x8*)(lds + PG8_SA(b, h) + aoff + m * 2048 + k * 1024); } while (0)
; #define PG8_LDB(dst, b, h) do { _Pragma("unroll") for (int n = 0; n < 2; ++n) _Pragma("unroll") for (int k = 0; k < 2; ++k) dst[n][k] = *(const PG8_LAS bf16x8*)(lds + PG8_SB(b, h) + boff + n * 2048 + k * 1024); } while (0)
; #define PG8_MMA(ai, bj, At, Bt) do { __builtin_amdgcn_s_setprio(1); _Pragma("unroll") for (int m = 0; m < 4; ++m) _Pragma("unroll") for (int n = 0; n < 2; ++n) _Pragma("unroll") for (int k = 0; k < 2; ++k) \
;         acc[ai][bj][m][n] = __builtin_amdgcn_mfma_f32_16x16x32_bf16(Bt[n][k], At[m][k], acc[ai][bj][m][n], 0, 0, 0); __builtin_amdgcn_s_setprio(0); } while (0)
; #define PG8_WAIT_V(n) asm volatile("s_waitcnt vmcnt(" #n ")" ::: "memory")
; #define PG8_BAR __builtin_amdgcn_s_barrier()
; template <class Epi, class Sched, bool ALIGN_EPI = false, bool SP2 = false>
; __device__ __forceinline__ void gemm_phase(PG8_LAS unsigned char* lds, const Gemm g, const Sched& S, const Epi& E) {
;     ...
;         for (int t = 0; t < nt; t += 2) {
;             if constexpr (Epi::MIDSCALE) { if (t == (nt >> 1)) E.midscale(acc, cur, wr, fr, ui); }
;             const bool last = (t == nt - 2);
;             const char* a1 = cA + (size_t)(t >> 1) * apair + kstep;
;             const char* a2 = last ? nA : cA + (size_t)((t >> 1) + 1) * apair; const char* b2 = last ? nB : cB + (size_t)(t + 2) * kstep;
;             const char* a3 = a2 + kstep; const char* b3 = b2 + kstep;
;             if (last && has_next) S.a_ready(nxt, ui + 1);
;             if constexpr (SP2) {
;             PG8_LDB(B0, 0, 0); PG8_LDB(B1, 0, 1); PG8_SCHED; PG8_LDA(At, 0, 0); PG8_STAGE(PG8_SA(1, 1), a1 + hstepA, voffA);
;             PG8_WAIT_V(8); PG8_WAIT_L(0); PG8_BAR; PG8_MMA(0, 0, At, B0); PG8_MMA(0, 1, At, B1); PG8_BAR; PG8_SCHED;
;             PG8_LDA(At, 0, 1); PG8_STAGE(PG8_SB(0, 0), b2, voffB); PG8_STAGE(PG8_SB(0, 1), b2 + hstep, voffB); PG8_STAGE(PG8_SA(0, 0), a2, voffA);
.LBB0_246:
	s_add_u32 s12, s10, 0xfffc0080
	s_addc_u32 s13, s11, -1
	s_add_i32 s94, 0, 0x10000
	s_cmp_eq_u32 vcc_lo, 12
	s_cselect_b32 s45, s21, s13
	s_cselect_b32 s44, s28, s12
	v_add_u32_e32 v0, s94, v179
	s_cselect_b32 s13, s43, s63
	s_cselect_b32 s12, s46, s47
	s_add_i32 vcc_hi, 0, 0x14000
	ds_read_b128 v[130:133], v0
	ds_read_b128 v[134:137], v0 offset:1024
	ds_read_b128 v[138:141], v0 offset:2048
	ds_read_b128 v[142:145], v0 offset:3072
	v_add_u32_e32 v0, vcc_hi, v179
	ds_read_b128 v[146:149], v0
	ds_read_b128 v[170:173], v0 offset:1024
	ds_read_b128 v[190:193], v0 offset:2048
	ds_read_b128 v[194:197], v0 offset:3072
	v_lshl_add_u64 v[150:151], s[10:11], 0, v[162:163]
	s_add_i32 m0, s17, 0xc000
	ds_read_b128 v[198:201], v186
	ds_read_b128 v[202:205], v186 offset:1024
	ds_read_b128 v[206:209], v186 offset:2048
	ds_read_b128 v[210:213], v186 offset:3072
	ds_read_b128 v[214:217], v186 offset:4096
	ds_read_b128 v[218:221], v186 offset:5120
	ds_read_b128 v[222:225], v186 offset:6144
	ds_read_b128 v[226:229], v186 offset:7168
	global_load_lds_dwordx4 v[150:151], off
	v_lshl_add_u64 v[150:151], s[10:11], 0, v[164:165]
	s_add_i32 m0, s17, 0xe000
	s_nop 0
	global_load_lds_dwordx4 v[150:151], off
	s_waitcnt vmcnt(8)
	s_waitcnt lgkmcnt(0)
	s_barrier
	s_setprio 1
	v_mfma_f32_16x16x32_bf16 v[126:129], v[130:133], v[198:201], v[126:129]
	v_mfma_f32_16x16x32_bf16 v[122:125], v[138:141], v[198:201], v[122:125]
	v_mfma_f32_16x16x32_bf16 v[110:113], v[130:133], v[206:209], v[110:113]
	v_mfma_f32_16x16x32_bf16 v[106:109], v[138:141], v[206:209], v[106:109]
	v_mfma_f32_16x16x32_bf16 v[94:97], v[130:133], v[214:217], v[94:97]
	v_mfma_f32_16x16x32_bf16 v[90:93], v[138:141], v[214:217], v[90:93]
	v_mfma_f32_16x16x32_bf16 v[78:81], v[130:133], v[222:225], v[78:81]
	v_mfma_f32_16x16x32_bf16 v[74:77], v[138:141], v[222:225], v[74:77]
	v_mfma_f32_16x16x32_bf16 v[126:129], v[134:137], v[202:205], v[126:129]
	v_mfma_f32_16x16x32_bf16 v[122:125], v[142:145], v[202:205], v[122:125]
	v_mfma_f32_16x16x32_bf16 v[110:113], v[134:137], v[210:213], v[110:113]
	v_mfma_f32_16x16x32_bf16 v[106:109], v[142:145], v[210:213], v[106:109]
	v_mfma_f32_16x16x32_bf16 v[94:97], v[134:137], v[218:221], v[94:97]
	v_mfma_f32_16x16x32_bf16 v[90:93], v[142:145], v[218:221], v[90:93]
	v_mfma_f32_16x16x32_bf16 v[78:81], v[134:137], v[226:229], v[78:81]
	v_mfma_f32_16x16x32_bf16 v[74:77], v[142:145], v[226:229], v[74:77]
	s_setprio 0
	s_setprio 1
	v_mfma_f32_16x16x32_bf16 v[118:121], v[146:149], v[198:201], v[118:121]
	v_mfma_f32_16x16x32_bf16 v[114:117], v[190:193], v[198:201], v[114:117]
	v_mfma_f32_16x16x32_bf16 v[102:105], v[146:149], v[206:209], v[102:105]
	v_mfma_f32_16x16x32_bf16 v[98:101], v[190:193], v[206:209], v[98:101]
	v_mfma_f32_16x16x32_bf16 v[86:89], v[146:149], v[214:217], v[86:89]
	v_mfma_f32_16x16x32_bf16 v[82:85], v[190:193], v[214:217], v[82:85]
	v_mfma_f32_16x16x32_bf16 v[70:73], v[146:149], v[222:225], v[70:73]
	v_mfma_f32_16x16x32_bf16 v[66:69], v[190:193], v[222:225], v[66:69]
	v_mfma_f32_16x16x32_bf16 v[118:121], v[170:173], v[202:205], v[118:121]
	v_mfma_f32_16x16x32_bf16 v[114:117], v[194:197], v[202:205], v[114:117]
	v_mfma_f32_16x16x32_bf16 v[102:105], v[170:173], v[210:213], v[102:105]
	v_mfma_f32_16x16x32_bf16 v[98:101], v[194:197], v[210:213], v[98:101]
	v_mfma_f32_16x16x32_bf16 v[86:89], v[170:173], v[218:221], v[86:89]
	v_mfma_f32_16x16x32_bf16 v[82:85], v[194:197], v[218:221], v[82:85]
	v_mfma_f32_16x16x32_bf16 v[70:73], v[170:173], v[226:229], v[70:73]
	v_mfma_f32_16x16x32_bf16 v[66:69], v[194:197], v[226:229], v[66:69]
	s_setprio 0
	s_barrier
	s_add_i32 s94, s94, s16
	v_lshl_add_u64 v[150:151], s[12:13], 0, v[156:157]
	s_mov_b32 m0, s94
	ds_read_b128 v[198:201], v186 offset:16384
	ds_read_b128 v[202:205], v186 offset:17408
	ds_read_b128 v[206:209], v186 offset:18432
	ds_read_b128 v[210:213], v186 offset:19456
	ds_read_b128 v[214:217], v186 offset:20480
	ds_read_b128 v[218:221], v186 offset:21504
	ds_read_b128 v[222:225], v186 offset:22528
	ds_read_b128 v[226:229], v186 offset:23552
	global_load_lds_dwordx4 v[150:151], off
	s_add_i32 m0, s94, 0x2000
	s_add_u32 s94, s12, 0x40000
	v_lshl_add_u64 v[166:167], s[12:13], 0, v[160:161]
	s_addc_u32 s95, s13, 0
	s_add_i32 vcc_hi, vcc_hi, s16
	global_load_lds_dwordx4 v[166:167], off
	v_lshl_add_u64 v[230:231], s[94:95], 0, v[156:157]
	s_mov_b32 m0, vcc_hi
	v_lshl_add_u64 v[232:233], s[44:45], 0, v[158:159]
	global_load_lds_dwordx4 v[230:231], off
	v_lshl_add_u64 v[230:231], s[94:95], 0, v[160:161]
	s_add_i32 m0, vcc_hi, 0x2000
	s_nop 0
	global_load_lds_dwordx4 v[230:231], off
	v_lshl_add_u64 v[230:231], s[44:45], 0, v[154:155]
	s_mov_b32 m0, s17
	s_nop 0
	global_load_lds_dwordx4 v[230:231], off
	s_mov_b32 m0, s51
	s_nop 0
	global_load_lds_dwordx4 v[232:233], off
	s_waitcnt vmcnt(8)
	s_waitcnt lgkmcnt(0)
	s_barrier
; #define PG8_STAGE(bufoff, gbase, voff) do { _Pragma("unroll") for (int _i = 0; _i < 2; ++_i) \
;         __builtin_amdgcn_global_load_lds((const unsigned*)((const char*)(gbase) + (voff)[_i]), (PG8_LAS unsigned*)(lds + (bufoff) + ldsw + _i * 8192), 16, 0, 0); } while (0)
; #define PG8_LDA(dst, b, h) do { _Pragma("unroll") for (int m = 0; m < 4; ++m) _Pragma("unroll") for (int k = 0; k < 2; ++k) dst[m][k] = *(const PG8_LAS bf16x8*)(lds + PG8_SA(b, h) + aoff + m * 2048 + k * 1024); } while (0)
; #define PG8_LDB(dst, b, h) do { _Pragma("unroll") for (int n = 0; n < 2; ++n) _Pragma("unroll") for (int k = 0; k < 2; ++k) dst[n][k] = *(const PG8_LAS bf16x8*)(lds + PG8_SB(b, h) + boff + n * 2048 + k * 1024); } while (0)
; #define PG8_MMA(ai, bj, At, Bt) do { __builtin_amdgcn_s_setprio(1); _Pragma("unroll") for (int m = 0; m < 4; ++m) _Pragma("unroll") for (int n = 0; n < 2; ++n) _Pragma("unroll") for (int k = 0; k < 2; ++k) \
;         acc[ai][bj][m][n] = __builtin_amdgcn_mfma_f32_16x16x32_bf16(Bt[n][k], At[m][k], acc[ai][bj][m][n], 0, 0, 0); __builtin_amdgcn_s_setprio(0); } while (0)
; #define PG8_WAIT_V(n) asm volatile("s_waitcnt vmcnt(" #n ")" ::: "memory")
; #define PG8_WAIT_L(n) asm volatile("s_waitcnt lgkmcnt(" #n ")" ::: "memory")
; #define PG8_BAR __builtin_amdgcn_s_barrier()
; #define PG8_SCHED __builtin_amdgcn_sched_barrier(0)
; template <class Epi, class Sched, bool ALIGN_EPI = false, bool SP2 = false>
; __device__ __forceinline__ void gemm_phase(PG8_LAS unsigned char* lds, const Gemm g, const Sched& S, const Epi& E) {
;     ...
;             PG8_WAIT_V(8); PG8_WAIT_L(0); PG8_BAR; PG8_MMA(1, 0, At, B0); PG8_MMA(1, 1, At, B1); PG8_BAR; PG8_SCHED;
;             PG8_LDB(B0, 1, 0); PG8_LDB(B1, 1, 1); PG8_SCHED; PG8_LDA(At, 1, 0); PG8_STAGE(PG8_SA(0, 1), a2 + hstepA, voffA);
;             PG8_WAIT_V(8); PG8_WAIT_L(0); PG8_BAR; PG8_MMA(0, 0, At, B0); PG8_MMA(0, 1, At, B1); PG8_BAR; PG8_SCHED;
	s_setprio 1
	v_mfma_f32_16x16x32_bf16 v[62:65], v[130:133], v[198:201], v[62:65]
	v_mfma_f32_16x16x32_bf16 v[58:61], v[138:141], v[198:201], v[58:61]
	v_mfma_f32_16x16x32_bf16 v[46:49], v[130:133], v[206:209], v[46:49]
	v_mfma_f32_16x16x32_bf16 v[42:45], v[138:141], v[206:209], v[42:45]
	v_mfma_f32_16x16x32_bf16 v[30:33], v[130:133], v[214:217], v[30:33]
	v_mfma_f32_16x16x32_bf16 v[26:29], v[138:141], v[214:217], v[26:29]
	v_mfma_f32_16x16x32_bf16 v[14:17], v[130:133], v[222:225], v[14:17]
	v_mfma_f32_16x16x32_bf16 v[10:13], v[138:141], v[222:225], v[10:13]
	v_mfma_f32_16x16x32_bf16 v[62:65], v[134:137], v[202:205], v[62:65]
	v_mfma_f32_16x16x32_bf16 v[58:61], v[142:145], v[202:205], v[58:61]
	v_mfma_f32_16x16x32_bf16 v[46:49], v[134:137], v[210:213], v[46:49]
	v_mfma_f32_16x16x32_bf16 v[42:45], v[142:145], v[210:213], v[42:45]
	v_mfma_f32_16x16x32_bf16 v[30:33], v[134:137], v[218:221], v[30:33]
	v_mfma_f32_16x16x32_bf16 v[26:29], v[142:145], v[218:221], v[26:29]
	v_mfma_f32_16x16x32_bf16 v[14:17], v[134:137], v[226:229], v[14:17]
	v_mfma_f32_16x16x32_bf16 v[10:13], v[142:145], v[226:229], v[10:13]
	s_setprio 0
	s_setprio 1
	v_mfma_f32_16x16x32_bf16 v[54:57], v[146:149], v[198:201], v[54:57]
	v_mfma_f32_16x16x32_bf16 v[50:53], v[190:193], v[198:201], v[50:53]
	v_mfma_f32_16x16x32_bf16 v[38:41], v[146:149], v[206:209], v[38:41]
	v_mfma_f32_16x16x32_bf16 v[34:37], v[190:193], v[206:209], v[34:37]
	v_mfma_f32_16x16x32_bf16 v[22:25], v[146:149], v[214:217], v[22:25]
	v_mfma_f32_16x16x32_bf16 v[18:21], v[190:193], v[214:217], v[18:21]
	v_mfma_f32_16x16x32_bf16 v[6:9], v[146:149], v[222:225], v[6:9]
	v_mfma_f32_16x16x32_bf16 v[2:5], v[190:193], v[222:225], v[2:5]
	v_mfma_f32_16x16x32_bf16 v[54:57], v[170:173], v[202:205], v[54:57]
	v_mfma_f32_16x16x32_bf16 v[50:53], v[194:197], v[202:205], v[50:53]
	v_mfma_f32_16x16x32_bf16 v[38:41], v[170:173], v[210:213], v[38:41]
	v_mfma_f32_16x16x32_bf16 v[34:37], v[194:197], v[210:213], v[34:37]
	v_mfma_f32_16x16x32_bf16 v[22:25], v[170:173], v[218:221], v[22:25]
	v_mfma_f32_16x16x32_bf16 v[18:21], v[194:197], v[218:221], v[18:21]
	v_mfma_f32_16x16x32_bf16 v[6:9], v[170:173], v[226:229], v[6:9]
	v_mfma_f32_16x16x32_bf16 v[2:5], v[194:197], v[226:229], v[2:5]
	s_setprio 0
	s_barrier
	s_add_i32 s94, 0, 0x18000
	v_add_u32_e32 v0, s94, v179
	s_add_i32 s95, 0, 0x1c000
	ds_read_b128 v[130:133], v0
	ds_read_b128 v[134:137], v0 offset:1024
	ds_read_b128 v[138:141], v0 offset:2048
	ds_read_b128 v[142:145], v0 offset:3072
	v_add_u32_e32 v0, s95, v179
	ds_read_b128 v[146:149], v0
	ds_read_b128 v[170:173], v0 offset:1024
	ds_read_b128 v[190:193], v0 offset:2048
	ds_read_b128 v[194:197], v0 offset:3072
	s_add_u32 s44, s44, 0x40000
	s_addc_u32 s45, s45, 0
	s_mov_b32 m0, s35
	v_lshl_add_u64 v[234:235], s[44:45], 0, v[154:155]
	ds_read_b128 v[198:201], v186 offset:32768
	ds_read_b128 v[202:205], v186 offset:33792
	ds_read_b128 v[206:209], v186 offset:34816
	ds_read_b128 v[210:213], v186 offset:35840
	ds_read_b128 v[214:217], v186 offset:36864
	ds_read_b128 v[218:221], v186 offset:37888
	ds_read_b128 v[222:225], v186 offset:38912
	ds_read_b128 v[226:229], v186 offset:39936
	global_load_lds_dwordx4 v[234:235], off
	v_lshl_add_u64 v[234:235], s[44:45], 0, v[158:159]
	s_mov_b32 m0, s30
	s_nop 0
	global_load_lds_dwordx4 v[234:235], off
	s_waitcnt vmcnt(8)
	s_waitcnt lgkmcnt(0)
	s_barrier
	s_setprio 1
	v_mfma_f32_16x16x32_bf16 v[126:129], v[130:133], v[198:201], v[126:129]
	v_mfma_f32_16x16x32_bf16 v[122:125], v[138:141], v[198:201], v[122:125]
	v_mfma_f32_16x16x32_bf16 v[110:113], v[130:133], v[206:209], v[110:113]
	v_mfma_f32_16x16x32_bf16 v[106:109], v[138:141], v[206:209], v[106:109]
	v_mfma_f32_16x16x32_bf16 v[94:97], v[130:133], v[214:217], v[94:97]
	v_mfma_f32_16x16x32_bf16 v[90:93], v[138:141], v[214:217], v[90:93]
	v_mfma_f32_16x16x32_bf16 v[78:81], v[130:133], v[222:225], v[78:81]
	v_mfma_f32_16x16x32_bf16 v[74:77], v[138:141], v[222:225], v[74:77]
	v_mfma_f32_16x16x32_bf16 v[126:129], v[134:137], v[202:205], v[126:129]
	v_mfma_f32_16x16x32_bf16 v[122:125], v[142:145], v[202:205], v[122:125]
	v_mfma_f32_16x16x32_bf16 v[110:113], v[134:137], v[210:213], v[110:113]
	v_mfma_f32_16x16x32_bf16 v[106:109], v[142:145], v[210:213], v[106:109]
	v_mfma_f32_16x16x32_bf16 v[94:97], v[134:137], v[218:221], v[94:97]
	v_mfma_f32_16x16x32_bf16 v[90:93], v[142:145], v[218:221], v[90:93]
	v_mfma_f32_16x16x32_bf16 v[78:81], v[134:137], v[226:229], v[78:81]
	v_mfma_f32_16x16x32_bf16 v[74:77], v[142:145], v[226:229], v[74:77]
	s_setprio 0
	s_setprio 1
	v_mfma_f32_16x16x32_bf16 v[118:121], v[146:149], v[198:201], v[118:121]
	v_mfma_f32_16x16x32_bf16 v[114:117], v[190:193], v[198:201], v[114:117]
	v_mfma_f32_16x16x32_bf16 v[102:105], v[146:149], v[206:209], v[102:105]
	v_mfma_f32_16x16x32_bf16 v[98:101], v[190:193], v[206:209], v[98:101]
	v_mfma_f32_16x16x32_bf16 v[86:89], v[146:149], v[214:217], v[86:89]
	v_mfma_f32_16x16x32_bf16 v[82:85], v[190:193], v[214:217], v[82:85]
	v_mfma_f32_16x16x32_bf16 v[70:73], v[146:149], v[222:225], v[70:73]
	v_mfma_f32_16x16x32_bf16 v[66:69], v[190:193], v[222:225], v[66:69]
	v_mfma_f32_16x16x32_bf16 v[118:121], v[170:173], v[202:205], v[118:121]
	v_mfma_f32_16x16x32_bf16 v[114:117], v[194:197], v[202:205], v[114:117]
	v_mfma_f32_16x16x32_bf16 v[102:105], v[170:173], v[210:213], v[102:105]
	v_mfma_f32_16x16x32_bf16 v[98:101], v[194:197], v[210:213], v[98:101]
	v_mfma_f32_16x16x32_bf16 v[86:89], v[170:173], v[218:221], v[86:89]
	v_mfma_f32_16x16x32_bf16 v[82:85], v[194:197], v[218:221], v[82:85]
	v_mfma_f32_16x16x32_bf16 v[70:73], v[170:173], v[226:229], v[70:73]
	v_mfma_f32_16x16x32_bf16 v[66:69], v[194:197], v[226:229], v[66:69]
	s_setprio 0
	s_barrier
; #define PG8_STAGE(bufoff, gbase, voff) do { _Pragma("unroll") for (int _i = 0; _i < 2; ++_i) \
;         __builtin_amdgcn_global_load_lds((const unsigned*)((const char*)(gbase) + (voff)[_i]), (PG8_LAS unsigned*)(lds + (bufoff) + ldsw + _i * 8192), 16, 0, 0); } while (0)
; #define PG8_LDA(dst, b, h) do { _Pragma("unroll") for (int m = 0; m < 4; ++m) _Pragma("unroll") for (int k = 0; k < 2; ++k) dst[m][k] = *(const PG8_LAS bf16x8*)(lds + PG8_SA(b, h) + aoff + m * 2048 + k * 1024); } while (0)
; #define PG8_MMA(ai, bj, At, Bt) do { __builtin_amdgcn_s_setprio(1); _Pragma("unroll") for (int m = 0; m < 4; ++m) _Pragma("unroll") for (int n = 0; n < 2; ++n) _Pragma("unroll") for (int k = 0; k < 2; ++k) \
;         acc[ai][bj][m][n] = __builtin_amdgcn_mfma_f32_16x16x32_bf16(Bt[n][k], At[m][k], acc[ai][bj][m][n], 0, 0, 0); __builtin_amdgcn_s_setprio(0); } while (0)
; #define PG8_WAIT_V(n) asm volatile("s_waitcnt vmcnt(" #n ")" ::: "memory")
; #define PG8_WAIT_L(n) asm volatile("s_waitcnt lgkmcnt(" #n ")" ::: "memory")
; #define PG8_BAR __builtin_amdgcn_s_barrier()
; #define PG8_SCHED __builtin_amdgcn_sched_barrier(0)
; template <class Epi, class Sched, bool ALIGN_EPI = false, bool SP2 = false>
; __device__ __forceinline__ void gemm_phase(PG8_LAS unsigned char* lds, const Gemm g, const Sched& S, const Epi& E) {
;     ...
;             PG8_LDA(At, 1, 1); PG8_STAGE(PG8_SB(1, 0), b3, voffB); PG8_STAGE(PG8_SB(1, 1), b3 + hstep, voffB); PG8_STAGE(PG8_SA(1, 0), a3, voffA);
;             PG8_WAIT_V(8); PG8_WAIT_L(0); PG8_BAR; PG8_MMA(1, 0, At, B0); PG8_MMA(1, 1, At, B1); PG8_BAR; PG8_SCHED;
	s_add_i32 s44, s94, s16
	v_lshl_add_u64 v[150:151], v[150:151], 0, s[48:49]
	s_mov_b32 m0, s44
	ds_read_b128 v[198:201], v186 offset:49152
	ds_read_b128 v[202:205], v186 offset:50176
	ds_read_b128 v[206:209], v186 offset:51200
	ds_read_b128 v[210:213], v186 offset:52224
	ds_read_b128 v[214:217], v186 offset:53248
	ds_read_b128 v[218:221], v186 offset:54272
	ds_read_b128 v[222:225], v186 offset:55296
	ds_read_b128 v[226:229], v186 offset:56320
	global_load_lds_dwordx4 v[150:151], off
	s_add_i32 m0, s44, 0x2000
	s_add_u32 s12, s12, 0x40080
	v_lshl_add_u64 v[150:151], v[166:167], 0, s[48:49]
	s_addc_u32 s13, s13, 0
	s_add_i32 s44, s95, s16
	global_load_lds_dwordx4 v[150:151], off
	v_lshl_add_u64 v[150:151], s[12:13], 0, v[156:157]
	s_mov_b32 m0, s44
	s_nop 0
	global_load_lds_dwordx4 v[150:151], off
	v_lshl_add_u64 v[150:151], s[12:13], 0, v[160:161]
	s_add_i32 m0, s44, 0x2000
	s_nop 0
	global_load_lds_dwordx4 v[150:151], off
	v_lshl_add_u64 v[150:151], v[230:231], 0, s[48:49]
	s_mov_b32 m0, s59
	s_nop 0
	global_load_lds_dwordx4 v[150:151], off
	v_lshl_add_u64 v[150:151], v[232:233], 0, s[48:49]
	s_mov_b32 m0, s86
	s_nop 0
	global_load_lds_dwordx4 v[150:151], off
	s_waitcnt vmcnt(8)
	s_waitcnt lgkmcnt(0)
	s_barrier
	s_setprio 1
	v_mfma_f32_16x16x32_bf16 v[62:65], v[130:133], v[198:201], v[62:65]
	v_mfma_f32_16x16x32_bf16 v[58:61], v[138:141], v[198:201], v[58:61]
	v_mfma_f32_16x16x32_bf16 v[46:49], v[130:133], v[206:209], v[46:49]
	v_mfma_f32_16x16x32_bf16 v[42:45], v[138:141], v[206:209], v[42:45]
	v_mfma_f32_16x16x32_bf16 v[30:33], v[130:133], v[214:217], v[30:33]
	v_mfma_f32_16x16x32_bf16 v[26:29], v[138:141], v[214:217], v[26:29]
	v_mfma_f32_16x16x32_bf16 v[14:17], v[130:133], v[222:225], v[14:17]
	v_mfma_f32_16x16x32_bf16 v[10:13], v[138:141], v[222:225], v[10:13]
	v_mfma_f32_16x16x32_bf16 v[62:65], v[134:137], v[202:205], v[62:65]
	v_mfma_f32_16x16x32_bf16 v[58:61], v[142:145], v[202:205], v[58:61]
	v_mfma_f32_16x16x32_bf16 v[46:49], v[134:137], v[210:213], v[46:49]
	v_mfma_f32_16x16x32_bf16 v[42:45], v[142:145], v[210:213], v[42:45]
	v_mfma_f32_16x16x32_bf16 v[30:33], v[134:137], v[218:221], v[30:33]
	v_mfma_f32_16x16x32_bf16 v[26:29], v[142:145], v[218:221], v[26:29]
	v_mfma_f32_16x16x32_bf16 v[14:17], v[134:137], v[226:229], v[14:17]
	v_mfma_f32_16x16x32_bf16 v[10:13], v[142:145], v[226:229], v[10:13]
	s_setprio 0
	s_setprio 1
	v_mfma_f32_16x16x32_bf16 v[54:57], v[146:149], v[198:201], v[54:57]
	v_mfma_f32_16x16x32_bf16 v[50:53], v[190:193], v[198:201], v[50:53]
	v_mfma_f32_16x16x32_bf16 v[38:41], v[146:149], v[206:209], v[38:41]
	v_mfma_f32_16x16x32_bf16 v[34:37], v[190:193], v[206:209], v[34:37]
	v_mfma_f32_16x16x32_bf16 v[22:25], v[146:149], v[214:217], v[22:25]
	v_mfma_f32_16x16x32_bf16 v[18:21], v[190:193], v[214:217], v[18:21]
	v_mfma_f32_16x16x32_bf16 v[6:9], v[146:149], v[222:225], v[6:9]
	v_mfma_f32_16x16x32_bf16 v[2:5], v[190:193], v[222:225], v[2:5]
	v_mfma_f32_16x16x32_bf16 v[54:57], v[170:173], v[202:205], v[54:57]
	v_mfma_f32_16x16x32_bf16 v[50:53], v[194:197], v[202:205], v[50:53]
	v_mfma_f32_16x16x32_bf16 v[38:41], v[170:173], v[210:213], v[38:41]
	v_mfma_f32_16x16x32_bf16 v[34:37], v[194:197], v[210:213], v[34:37]
	v_mfma_f32_16x16x32_bf16 v[22:25], v[170:173], v[218:221], v[22:25]
	v_mfma_f32_16x16x32_bf16 v[18:21], v[194:197], v[218:221], v[18:21]
	v_mfma_f32_16x16x32_bf16 v[6:9], v[170:173], v[226:229], v[6:9]
	v_mfma_f32_16x16x32_bf16 v[2:5], v[194:197], v[226:229], v[2:5]
	s_setprio 0
	s_barrier
	s_add_i32 vcc_lo, vcc_lo, 2
	s_add_u32 s10, s10, 0x100
	s_addc_u32 s11, s11, 0
	s_add_u32 s47, s47, 0x100
	s_addc_u32 s63, s63, 0
	s_cmp_gt_u32 vcc_lo, 13
	s_cbranch_scc0 .LBB0_246
	s_and_b64 vcc, exec, s[88:89]
	s_cbranch_vccz .LBB0_249
	s_barrier

; #define PG8_STAGE(bufoff, gbase, voff) do { _Pragma("unroll") for (int _i = 0; _i < 2; ++_i) \
;         __builtin_amdgcn_global_load_lds((const unsigned*)((const char*)(gbase) + (voff)[_i]), (PG8_LAS unsigned*)(lds + (bufoff) + ldsw + _i * 8192), 16, 0, 0); } while (0)
; #define PG8_LDA(dst, b, h) do { _Pragma("unroll") for (int m = 0; m < 4; ++m) _Pragma("unroll") for (int k = 0; k < 2; ++k) dst[m][k] = *(const PG8_LAS bf16x8*)(lds + PG8_SA(b, h) + aoff + m * 2048 + k * 1024); } while (0)
; #define PG8_LDB(dst, b, h) do { _Pragma("unroll") for (int n = 0; n < 2; ++n) _Pragma("unroll") for (int k = 0; k < 2; ++k) dst[n][k] = *(const PG8_LAS bf16x8*)(lds + PG8_SB(b, h) + boff + n * 2048 + k * 1024); } while (0)
; #define PG8_MMA(ai, bj, At, Bt) do { __builtin_amdgcn_s_setprio(1); _Pragma("unroll") for (int m = 0; m < 4; ++m) _Pragma("unroll") for (int n = 0; n < 2; ++n) _Pragma("unroll") for (int k = 0; k < 2; ++k) \
;         acc[ai][bj][m][n] = __builtin_amdgcn_mfma_f32_16x16x32_bf16(Bt[n][k], At[m][k], acc[ai][bj][m][n], 0, 0, 0); __builtin_amdgcn_s_setprio(0); } while (0)
; template <class Epi, class Sched, bool ALIGN_EPI = false, bool SP2 = false>
; __device__ __forceinline__ void gemm_phase(PG8_LAS unsigned char* lds, const Gemm g, const Sched& S, const Epi& E) {
;     ...
;         for (int t = 0; t < nt; t += 2) {
;             if constexpr (Epi::MIDSCALE) { if (t == (nt >> 1)) E.midscale(acc, cur, wr, fr, ui); }
;             const bool last = (t == nt - 2);
;             const char* a1 = cA + (size_t)(t >> 1) * apair + kstep;
;             const char* a2 = last ? nA : cA + (size_t)((t >> 1) + 1) * apair; const char* b2 = last ? nB : cB + (size_t)(t + 2) * kstep;
;             const char* a3 = a2 + kstep; const char* b3 = b2 + kstep;
;             if (last && has_next) S.a_ready(nxt, ui + 1);
;             if constexpr (SP2) {
;             PG8_LDB(B0, 0, 0); PG8_LDB(B1, 0, 1); PG8_SCHED; PG8_LDA(At, 0, 0); PG8_STAGE(PG8_SA(1, 1), a1 + hstepA, voffA);
;             PG8_WAIT_V(8); PG8_WAIT_L(0); PG8_BAR; PG8_MMA(0, 0, At, B0); PG8_MMA(0, 1, At, B1); PG8_BAR; PG8_SCHED;
;             PG8_LDA(At, 0, 1); PG8_STAGE(PG8_SB(0, 0), b2, voffB); PG8_STAGE(PG8_SB(0, 1), b2 + hstep, voffB); PG8_STAGE(PG8_SA(0, 0), a2, voffA);
;             PG8_WAIT_V(8); PG8_WAIT_L(0); PG8_BAR; PG8_MMA(1, 0, At, B0); PG8_MMA(1, 1, At, B1); PG8_BAR; PG8_SCHED;
.LBB0_386:
	s_add_u32 s66, s42, s64
	s_addc_u32 s67, s43, s65
	s_add_u32 s66, s66, 0x1080000
	s_addc_u32 s67, s67, 0
	s_and_b64 s[44:45], s[44:45], exec
	s_cselect_b32 s45, s51, s67
	s_cselect_b32 s44, s78, s66
	s_cselect_b32 s67, s79, s84
	s_cselect_b32 s66, s80, s83
	s_add_i32 s86, 0, 0x10000
	v_add_u32_e32 v0, s86, v154
	s_add_i32 s88, 0, 0x14000
	ds_read_b128 v[158:161], v0
	ds_read_b128 v[162:165], v0 offset:1024
	ds_read_b128 v[178:181], v0 offset:2048
	ds_read_b128 v[182:185], v0 offset:3072
	v_add_u32_e32 v0, s88, v154
	ds_read_b128 v[186:189], v0
	ds_read_b128 v[190:193], v0 offset:1024
	ds_read_b128 v[194:197], v0 offset:2048
	ds_read_b128 v[198:201], v0 offset:3072
	v_lshl_add_u64 v[2:3], v[144:145], 0, s[64:65]
	s_add_i32 m0, s35, 0xc000
	ds_read_b128 v[202:205], v156
	ds_read_b128 v[206:209], v156 offset:1024
	ds_read_b128 v[210:213], v156 offset:2048
	ds_read_b128 v[214:217], v156 offset:3072
	ds_read_b128 v[218:221], v156 offset:4096
	ds_read_b128 v[222:225], v156 offset:5120
	ds_read_b128 v[226:229], v156 offset:6144
	ds_read_b128 v[230:233], v156 offset:7168
	global_load_lds_dwordx4 v[2:3], off
	v_lshl_add_u64 v[2:3], v[146:147], 0, s[64:65]
	s_add_i32 m0, s35, 0xe000
	s_nop 0
	global_load_lds_dwordx4 v[2:3], off
	s_waitcnt vmcnt(8)
	s_waitcnt lgkmcnt(0)
	s_barrier
	s_setprio 1
	v_mfma_f32_16x16x32_bf16 v[128:131], v[158:161], v[202:205], v[128:131]
	v_mfma_f32_16x16x32_bf16 v[124:127], v[178:181], v[202:205], v[124:127]
	v_mfma_f32_16x16x32_bf16 v[112:115], v[158:161], v[210:213], v[112:115]
	v_mfma_f32_16x16x32_bf16 v[108:111], v[178:181], v[210:213], v[108:111]
	v_mfma_f32_16x16x32_bf16 v[96:99], v[158:161], v[218:221], v[96:99]
	v_mfma_f32_16x16x32_bf16 v[92:95], v[178:181], v[218:221], v[92:95]
	v_mfma_f32_16x16x32_bf16 v[80:83], v[158:161], v[226:229], v[80:83]
	v_mfma_f32_16x16x32_bf16 v[76:79], v[178:181], v[226:229], v[76:79]
	v_mfma_f32_16x16x32_bf16 v[128:131], v[162:165], v[206:209], v[128:131]
	v_mfma_f32_16x16x32_bf16 v[124:127], v[182:185], v[206:209], v[124:127]
	v_mfma_f32_16x16x32_bf16 v[112:115], v[162:165], v[214:217], v[112:115]
	v_mfma_f32_16x16x32_bf16 v[108:111], v[182:185], v[214:217], v[108:111]
	v_mfma_f32_16x16x32_bf16 v[96:99], v[162:165], v[222:225], v[96:99]
	v_mfma_f32_16x16x32_bf16 v[92:95], v[182:185], v[222:225], v[92:95]
	v_mfma_f32_16x16x32_bf16 v[80:83], v[162:165], v[230:233], v[80:83]
	v_mfma_f32_16x16x32_bf16 v[76:79], v[182:185], v[230:233], v[76:79]
	s_setprio 0
	s_setprio 1
	v_mfma_f32_16x16x32_bf16 v[120:123], v[186:189], v[202:205], v[120:123]
	v_mfma_f32_16x16x32_bf16 v[116:119], v[194:197], v[202:205], v[116:119]
	v_mfma_f32_16x16x32_bf16 v[104:107], v[186:189], v[210:213], v[104:107]
	v_mfma_f32_16x16x32_bf16 v[100:103], v[194:197], v[210:213], v[100:103]
	v_mfma_f32_16x16x32_bf16 v[88:91], v[186:189], v[218:221], v[88:91]
	v_mfma_f32_16x16x32_bf16 v[84:87], v[194:197], v[218:221], v[84:87]
	v_mfma_f32_16x16x32_bf16 v[72:75], v[186:189], v[226:229], v[72:75]
	v_mfma_f32_16x16x32_bf16 v[68:71], v[194:197], v[226:229], v[68:71]
	v_mfma_f32_16x16x32_bf16 v[120:123], v[190:193], v[206:209], v[120:123]
	v_mfma_f32_16x16x32_bf16 v[116:119], v[198:201], v[206:209], v[116:119]
	v_mfma_f32_16x16x32_bf16 v[104:107], v[190:193], v[214:217], v[104:107]
	v_mfma_f32_16x16x32_bf16 v[100:103], v[198:201], v[214:217], v[100:103]
	v_mfma_f32_16x16x32_bf16 v[88:91], v[190:193], v[222:225], v[88:91]
	v_mfma_f32_16x16x32_bf16 v[84:87], v[198:201], v[222:225], v[84:87]
	v_mfma_f32_16x16x32_bf16 v[72:75], v[190:193], v[230:233], v[72:75]
	v_mfma_f32_16x16x32_bf16 v[68:71], v[198:201], v[230:233], v[68:71]
	s_setprio 0
	s_barrier
	s_add_i32 s86, s86, s30
	v_lshl_add_u64 v[150:151], s[66:67], 0, v[134:135]
	s_mov_b32 m0, s86
	ds_read_b128 v[202:205], v156 offset:16384
	ds_read_b128 v[206:209], v156 offset:17408
	ds_read_b128 v[210:213], v156 offset:18432
	ds_read_b128 v[214:217], v156 offset:19456
	ds_read_b128 v[218:221], v156 offset:20480
	ds_read_b128 v[222:225], v156 offset:21504
	ds_read_b128 v[226:229], v156 offset:22528
	ds_read_b128 v[230:233], v156 offset:23552
	global_load_lds_dwordx4 v[150:151], off
	s_add_i32 m0, s86, 0x2000
	s_add_u32 s86, s66, 0x80000
	v_lshl_add_u64 v[166:167], s[66:67], 0, v[138:139]
	s_addc_u32 s87, s67, 0
	s_add_i32 s88, s88, s30
	global_load_lds_dwordx4 v[166:167], off
	v_lshl_add_u64 v[2:3], s[86:87], 0, v[134:135]
	s_mov_b32 m0, s88
	v_lshl_add_u64 v[170:171], s[44:45], 0, v[132:133]
	global_load_lds_dwordx4 v[2:3], off
	v_lshl_add_u64 v[2:3], s[86:87], 0, v[138:139]
	s_add_i32 m0, s88, 0x2000
	v_lshl_add_u64 v[172:173], s[44:45], 0, v[136:137]
	global_load_lds_dwordx4 v[2:3], off
	s_mov_b32 m0, s35
	s_nop 0
	global_load_lds_dwordx4 v[170:171], off
	s_mov_b32 m0, s46
	s_nop 0
	global_load_lds_dwordx4 v[172:173], off
	s_waitcnt vmcnt(8)
	s_waitcnt lgkmcnt(0)
	s_barrier
; #define PG8_STAGE(bufoff, gbase, voff) do { _Pragma("unroll") for (int _i = 0; _i < 2; ++_i) \
;         __builtin_amdgcn_global_load_lds((const unsigned*)((const char*)(gbase) + (voff)[_i]), (PG8_LAS unsigned*)(lds + (bufoff) + ldsw + _i * 8192), 16, 0, 0); } while (0)
; #define PG8_LDA(dst, b, h) do { _Pragma("unroll") for (int m = 0; m < 4; ++m) _Pragma("unroll") for (int k = 0; k < 2; ++k) dst[m][k] = *(const PG8_LAS bf16x8*)(lds + PG8_SA(b, h) + aoff + m * 2048 + k * 1024); } while (0)
; #define PG8_LDB(dst, b, h) do { _Pragma("unroll") for (int n = 0; n < 2; ++n) _Pragma("unroll") for (int k = 0; k < 2; ++k) dst[n][k] = *(const PG8_LAS bf16x8*)(lds + PG8_SB(b, h) + boff + n * 2048 + k * 1024); } while (0)
; #define PG8_MMA(ai, bj, At, Bt) do { __builtin_amdgcn_s_setprio(1); _Pragma("unroll") for (int m = 0; m < 4; ++m) _Pragma("unroll") for (int n = 0; n < 2; ++n) _Pragma("unroll") for (int k = 0; k < 2; ++k) \
;         acc[ai][bj][m][n] = __builtin_amdgcn_mfma_f32_16x16x32_bf16(Bt[n][k], At[m][k], acc[ai][bj][m][n], 0, 0, 0); __builtin_amdgcn_s_setprio(0); } while (0)
; template <class Epi, class Sched, bool ALIGN_EPI = false, bool SP2 = false>
; __device__ __forceinline__ void gemm_phase(PG8_LAS unsigned char* lds, const Gemm g, const Sched& S, const Epi& E) {
;     ...
;             if constexpr (SP2) {
;             PG8_LDB(B0, 0, 0); PG8_LDB(B1, 0, 1); PG8_SCHED; PG8_LDA(At, 0, 0); PG8_STAGE(PG8_SA(1, 1), a1 + hstepA, voffA);
;             PG8_WAIT_V(8); PG8_WAIT_L(0); PG8_BAR; PG8_MMA(0, 0, At, B0); PG8_MMA(0, 1, At, B1); PG8_BAR; PG8_SCHED;
;             PG8_LDA(At, 0, 1); PG8_STAGE(PG8_SB(0, 0), b2, voffB); PG8_STAGE(PG8_SB(0, 1), b2 + hstep, voffB); PG8_STAGE(PG8_SA(0, 0), a2, voffA);
;             PG8_WAIT_V(8); PG8_WAIT_L(0); PG8_BAR; PG8_MMA(1, 0, At, B0); PG8_MMA(1, 1, At, B1); PG8_BAR; PG8_SCHED;
;             PG8_LDB(B0, 1, 0); PG8_LDB(B1, 1, 1); PG8_SCHED; PG8_LDA(At, 1, 0); PG8_STAGE(PG8_SA(0, 1), a2 + hstepA, voffA);
;             PG8_WAIT_V(8); PG8_WAIT_L(0); PG8_BAR; PG8_MMA(0, 0, At, B0); PG8_MMA(0, 1, At, B1); PG8_BAR; PG8_SCHED;
;             PG8_LDA(At, 1, 1); PG8_STAGE(PG8_SB(1, 0), b3, voffB); PG8_STAGE(PG8_SB(1, 1), b3 + hstep, voffB); PG8_STAGE(PG8_SA(1, 0), a3, voffA);
;             PG8_WAIT_V(8); PG8_WAIT_L(0); PG8_BAR; PG8_MMA(1, 0, At, B0); PG8_MMA(1, 1, At, B1); PG8_BAR; PG8_SCHED;
	s_setprio 1
	v_mfma_f32_16x16x32_bf16 v[64:67], v[158:161], v[202:205], v[64:67]
	v_mfma_f32_16x16x32_bf16 v[60:63], v[178:181], v[202:205], v[60:63]
	v_mfma_f32_16x16x32_bf16 v[48:51], v[158:161], v[210:213], v[48:51]
	v_mfma_f32_16x16x32_bf16 v[44:47], v[178:181], v[210:213], v[44:47]
	v_mfma_f32_16x16x32_bf16 v[32:35], v[158:161], v[218:221], v[32:35]
	v_mfma_f32_16x16x32_bf16 v[28:31], v[178:181], v[218:221], v[28:31]
	v_mfma_f32_16x16x32_bf16 v[16:19], v[158:161], v[226:229], v[16:19]
	v_mfma_f32_16x16x32_bf16 v[12:15], v[178:181], v[226:229], v[12:15]
	v_mfma_f32_16x16x32_bf16 v[64:67], v[162:165], v[206:209], v[64:67]
	v_mfma_f32_16x16x32_bf16 v[60:63], v[182:185], v[206:209], v[60:63]
	v_mfma_f32_16x16x32_bf16 v[48:51], v[162:165], v[214:217], v[48:51]
	v_mfma_f32_16x16x32_bf16 v[44:47], v[182:185], v[214:217], v[44:47]
	v_mfma_f32_16x16x32_bf16 v[32:35], v[162:165], v[222:225], v[32:35]
	v_mfma_f32_16x16x32_bf16 v[28:31], v[182:185], v[222:225], v[28:31]
	v_mfma_f32_16x16x32_bf16 v[16:19], v[162:165], v[230:233], v[16:19]
	v_mfma_f32_16x16x32_bf16 v[12:15], v[182:185], v[230:233], v[12:15]
	s_setprio 0
	s_setprio 1
	v_mfma_f32_16x16x32_bf16 v[56:59], v[186:189], v[202:205], v[56:59]
	v_mfma_f32_16x16x32_bf16 v[52:55], v[194:197], v[202:205], v[52:55]
	v_mfma_f32_16x16x32_bf16 v[40:43], v[186:189], v[210:213], v[40:43]
	v_mfma_f32_16x16x32_bf16 v[36:39], v[194:197], v[210:213], v[36:39]
	v_mfma_f32_16x16x32_bf16 v[24:27], v[186:189], v[218:221], v[24:27]
	v_mfma_f32_16x16x32_bf16 v[20:23], v[194:197], v[218:221], v[20:23]
	v_mfma_f32_16x16x32_bf16 v[8:11], v[186:189], v[226:229], v[8:11]
	v_mfma_f32_16x16x32_bf16 v[2:5], v[194:197], v[226:229], v[4:7]
	v_mfma_f32_16x16x32_bf16 v[56:59], v[190:193], v[206:209], v[56:59]
	v_mfma_f32_16x16x32_bf16 v[52:55], v[198:201], v[206:209], v[52:55]
	v_mfma_f32_16x16x32_bf16 v[40:43], v[190:193], v[214:217], v[40:43]
	v_mfma_f32_16x16x32_bf16 v[36:39], v[198:201], v[214:217], v[36:39]
	v_mfma_f32_16x16x32_bf16 v[24:27], v[190:193], v[222:225], v[24:27]
	v_mfma_f32_16x16x32_bf16 v[20:23], v[198:201], v[222:225], v[20:23]
	v_mfma_f32_16x16x32_bf16 v[8:11], v[190:193], v[230:233], v[8:11]
	v_mfma_f32_16x16x32_bf16 v[2:5], v[198:201], v[230:233], v[2:5]
	s_setprio 0
	s_barrier
	s_add_i32 s86, 0, 0x18000
	v_add_u32_e32 v0, s86, v154
	s_add_i32 s87, 0, 0x1c000
	ds_read_b128 v[158:161], v0
	ds_read_b128 v[162:165], v0 offset:1024
	ds_read_b128 v[178:181], v0 offset:2048
	ds_read_b128 v[182:185], v0 offset:3072
	v_add_u32_e32 v0, s87, v154
	ds_read_b128 v[186:189], v0
	ds_read_b128 v[190:193], v0 offset:1024
	ds_read_b128 v[194:197], v0 offset:2048
	ds_read_b128 v[198:201], v0 offset:3072
	s_add_u32 s44, s44, 0x8000
	s_addc_u32 s45, s45, 0
	s_mov_b32 m0, s47
	v_lshl_add_u64 v[6:7], s[44:45], 0, v[132:133]
	ds_read_b128 v[202:205], v156 offset:32768
	ds_read_b128 v[206:209], v156 offset:33792
	ds_read_b128 v[210:213], v156 offset:34816
	ds_read_b128 v[214:217], v156 offset:35840
	ds_read_b128 v[218:221], v156 offset:36864
	ds_read_b128 v[222:225], v156 offset:37888
	ds_read_b128 v[226:229], v156 offset:38912
	ds_read_b128 v[230:233], v156 offset:39936
	global_load_lds_dwordx4 v[6:7], off
	v_lshl_add_u64 v[6:7], s[44:45], 0, v[136:137]
	s_mov_b32 m0, s68
	s_nop 0
	global_load_lds_dwordx4 v[6:7], off
	s_waitcnt vmcnt(8)
	s_waitcnt lgkmcnt(0)
	s_barrier
	s_setprio 1
	v_mfma_f32_16x16x32_bf16 v[128:131], v[158:161], v[202:205], v[128:131]
	v_mfma_f32_16x16x32_bf16 v[124:127], v[178:181], v[202:205], v[124:127]
	v_mfma_f32_16x16x32_bf16 v[112:115], v[158:161], v[210:213], v[112:115]
	v_mfma_f32_16x16x32_bf16 v[108:111], v[178:181], v[210:213], v[108:111]
	v_mfma_f32_16x16x32_bf16 v[96:99], v[158:161], v[218:221], v[96:99]
	v_mfma_f32_16x16x32_bf16 v[92:95], v[178:181], v[218:221], v[92:95]
	v_mfma_f32_16x16x32_bf16 v[80:83], v[158:161], v[226:229], v[80:83]
	v_mfma_f32_16x16x32_bf16 v[76:79], v[178:181], v[226:229], v[76:79]
	v_mfma_f32_16x16x32_bf16 v[128:131], v[162:165], v[206:209], v[128:131]
	v_mfma_f32_16x16x32_bf16 v[124:127], v[182:185], v[206:209], v[124:127]
	v_mfma_f32_16x16x32_bf16 v[112:115], v[162:165], v[214:217], v[112:115]
	v_mfma_f32_16x16x32_bf16 v[108:111], v[182:185], v[214:217], v[108:111]
	v_mfma_f32_16x16x32_bf16 v[96:99], v[162:165], v[222:225], v[96:99]
	v_mfma_f32_16x16x32_bf16 v[92:95], v[182:185], v[222:225], v[92:95]
	v_mfma_f32_16x16x32_bf16 v[80:83], v[162:165], v[230:233], v[80:83]
	v_mfma_f32_16x16x32_bf16 v[76:79], v[182:185], v[230:233], v[76:79]
	s_setprio 0
	s_setprio 1
	v_mfma_f32_16x16x32_bf16 v[120:123], v[186:189], v[202:205], v[120:123]
	v_mfma_f32_16x16x32_bf16 v[116:119], v[194:197], v[202:205], v[116:119]
	v_mfma_f32_16x16x32_bf16 v[104:107], v[186:189], v[210:213], v[104:107]
	v_mfma_f32_16x16x32_bf16 v[100:103], v[194:197], v[210:213], v[100:103]
	v_mfma_f32_16x16x32_bf16 v[88:91], v[186:189], v[218:221], v[88:91]
	v_mfma_f32_16x16x32_bf16 v[84:87], v[194:197], v[218:221], v[84:87]
	v_mfma_f32_16x16x32_bf16 v[72:75], v[186:189], v[226:229], v[72:75]
	v_mfma_f32_16x16x32_bf16 v[68:71], v[194:197], v[226:229], v[68:71]
	v_mfma_f32_16x16x32_bf16 v[120:123], v[190:193], v[206:209], v[120:123]
	v_mfma_f32_16x16x32_bf16 v[116:119], v[198:201], v[206:209], v[116:119]
	v_mfma_f32_16x16x32_bf16 v[104:107], v[190:193], v[214:217], v[104:107]
	v_mfma_f32_16x16x32_bf16 v[100:103], v[198:201], v[214:217], v[100:103]
	v_mfma_f32_16x16x32_bf16 v[88:91], v[190:193], v[222:225], v[88:91]
	v_mfma_f32_16x16x32_bf16 v[84:87], v[198:201], v[222:225], v[84:87]
	v_mfma_f32_16x16x32_bf16 v[72:75], v[190:193], v[230:233], v[72:75]
	v_mfma_f32_16x16x32_bf16 v[68:71], v[198:201], v[230:233], v[68:71]
	s_setprio 0
	s_barrier
; #define PG8_STAGE(bufoff, gbase, voff) do { _Pragma("unroll") for (int _i = 0; _i < 2; ++_i) \
;         __builtin_amdgcn_global_load_lds((const unsigned*)((const char*)(gbase) + (voff)[_i]), (PG8_LAS unsigned*)(lds + (bufoff) + ldsw + _i * 8192), 16, 0, 0); } while (0)
; #define PG8_LDA(dst, b, h) do { _Pragma("unroll") for (int m = 0; m < 4; ++m) _Pragma("unroll") for (int k = 0; k < 2; ++k) dst[m][k] = *(const PG8_LAS bf16x8*)(lds + PG8_SA(b, h) + aoff + m * 2048 + k * 1024); } while (0)
; #define PG8_WAIT_V(n) asm volatile("s_waitcnt vmcnt(" #n ")" ::: "memory")
; template <class Epi, class Sched, bool ALIGN_EPI = false, bool SP2 = false>
; __device__ __forceinline__ void gemm_phase(PG8_LAS unsigned char* lds, const Gemm g, const Sched& S, const Epi& E) {
;     ...
;         for (int t = 0; t < nt; t += 2) {
;             if constexpr (Epi::MIDSCALE) { if (t == (nt >> 1)) E.midscale(acc, cur, wr, fr, ui); }
;             const bool last = (t == nt - 2);
;             const char* a1 = cA + (size_t)(t >> 1) * apair + kstep;
;             const char* a2 = last ? nA : cA + (size_t)((t >> 1) + 1) * apair; const char* b2 = last ? nB : cB + (size_t)(t + 2) * kstep;
;             const char* a3 = a2 + kstep; const char* b3 = b2 + kstep;
;             if (last && has_next) S.a_ready(nxt, ui + 1);
;             if constexpr (SP2) {
;             PG8_LDB(B0, 0, 0); PG8_LDB(B1, 0, 1); PG8_SCHED; PG8_LDA(At, 0, 0); PG8_STAGE(PG8_SA(1, 1), a1 + hstepA, voffA);
;             PG8_WAIT_V(8); PG8_WAIT_L(0); PG8_BAR; PG8_MMA(0, 0, At, B0); PG8_MMA(0, 1, At, B1); PG8_BAR; PG8_SCHED;
;             PG8_LDA(At, 0, 1); PG8_STAGE(PG8_SB(0, 0), b2, voffB); PG8_STAGE(PG8_SB(0, 1), b2 + hstep, voffB); PG8_STAGE(PG8_SA(0, 0), a2, voffA);
;             PG8_WAIT_V(8); PG8_WAIT_L(0); PG8_BAR; PG8_MMA(1, 0, At, B0); PG8_MMA(1, 1, At, B1); PG8_BAR; PG8_SCHED;
;             PG8_LDB(B0, 1, 0); PG8_LDB(B1, 1, 1); PG8_SCHED; PG8_LDA(At, 1, 0); PG8_STAGE(PG8_SA(0, 1), a2 + hstepA, voffA);
;             PG8_WAIT_V(8); PG8_WAIT_L(0); PG8_BAR; PG8_MMA(0, 0, At, B0); PG8_MMA(0, 1, At, B1); PG8_BAR; PG8_SCHED;
;             PG8_LDA(At, 1, 1); PG8_STAGE(PG8_SB(1, 0), b3, voffB); PG8_STAGE(PG8_SB(1, 1), b3 + hstep, voffB); PG8_STAGE(PG8_SA(1, 0), a3, voffA);
;             PG8_WAIT_V(8); PG8_WAIT_L(0); PG8_BAR; PG8_MMA(1, 0, At, B0); PG8_MMA(1, 1, At, B1); PG8_BAR; PG8_SCHED;
	s_add_i32 s44, s86, s30
	v_lshl_add_u64 v[6:7], v[150:151], 0, s[48:49]
	s_mov_b32 m0, s44
	ds_read_b128 v[202:205], v156 offset:49152
	ds_read_b128 v[206:209], v156 offset:50176
	ds_read_b128 v[210:213], v156 offset:51200
	ds_read_b128 v[214:217], v156 offset:52224
	ds_read_b128 v[218:221], v156 offset:53248
	ds_read_b128 v[222:225], v156 offset:54272
	ds_read_b128 v[226:229], v156 offset:55296
	ds_read_b128 v[230:233], v156 offset:56320
	global_load_lds_dwordx4 v[6:7], off
	s_add_i32 m0, s44, 0x2000
	s_add_u32 s44, s66, 0x80080
	v_lshl_add_u64 v[6:7], v[166:167], 0, s[48:49]
	s_addc_u32 s45, s67, 0
	s_add_i32 s66, s87, s30
	global_load_lds_dwordx4 v[6:7], off
	v_lshl_add_u64 v[6:7], s[44:45], 0, v[134:135]
	s_mov_b32 m0, s66
	s_nop 0
	global_load_lds_dwordx4 v[6:7], off
	v_lshl_add_u64 v[6:7], s[44:45], 0, v[138:139]
	s_add_i32 m0, s66, 0x2000
	s_nop 0
	global_load_lds_dwordx4 v[6:7], off
	v_lshl_add_u64 v[6:7], v[170:171], 0, s[48:49]
	s_mov_b32 m0, s71
	s_nop 0
	global_load_lds_dwordx4 v[6:7], off
	v_lshl_add_u64 v[6:7], v[172:173], 0, s[48:49]
	s_mov_b32 m0, s72
	s_nop 0
	global_load_lds_dwordx4 v[6:7], off
	s_waitcnt vmcnt(8)
	s_waitcnt lgkmcnt(0)
	s_barrier
	s_setprio 1
	v_mfma_f32_16x16x32_bf16 v[64:67], v[158:161], v[202:205], v[64:67]
	v_mfma_f32_16x16x32_bf16 v[60:63], v[178:181], v[202:205], v[60:63]
	v_mfma_f32_16x16x32_bf16 v[48:51], v[158:161], v[210:213], v[48:51]
	v_mfma_f32_16x16x32_bf16 v[44:47], v[178:181], v[210:213], v[44:47]
	v_mfma_f32_16x16x32_bf16 v[32:35], v[158:161], v[218:221], v[32:35]
	v_mfma_f32_16x16x32_bf16 v[28:31], v[178:181], v[218:221], v[28:31]
	v_mfma_f32_16x16x32_bf16 v[16:19], v[158:161], v[226:229], v[16:19]
	v_mfma_f32_16x16x32_bf16 v[12:15], v[178:181], v[226:229], v[12:15]
	v_mfma_f32_16x16x32_bf16 v[64:67], v[162:165], v[206:209], v[64:67]
	v_mfma_f32_16x16x32_bf16 v[60:63], v[182:185], v[206:209], v[60:63]
	v_mfma_f32_16x16x32_bf16 v[48:51], v[162:165], v[214:217], v[48:51]
	v_mfma_f32_16x16x32_bf16 v[44:47], v[182:185], v[214:217], v[44:47]
	v_mfma_f32_16x16x32_bf16 v[32:35], v[162:165], v[222:225], v[32:35]
	v_mfma_f32_16x16x32_bf16 v[28:31], v[182:185], v[222:225], v[28:31]
	v_mfma_f32_16x16x32_bf16 v[16:19], v[162:165], v[230:233], v[16:19]
	v_mfma_f32_16x16x32_bf16 v[12:15], v[182:185], v[230:233], v[12:15]
	s_setprio 0
	s_setprio 1
	v_mfma_f32_16x16x32_bf16 v[56:59], v[186:189], v[202:205], v[56:59]
	v_mfma_f32_16x16x32_bf16 v[52:55], v[194:197], v[202:205], v[52:55]
	v_mfma_f32_16x16x32_bf16 v[40:43], v[186:189], v[210:213], v[40:43]
	v_mfma_f32_16x16x32_bf16 v[36:39], v[194:197], v[210:213], v[36:39]
	v_mfma_f32_16x16x32_bf16 v[24:27], v[186:189], v[218:221], v[24:27]
	v_mfma_f32_16x16x32_bf16 v[20:23], v[194:197], v[218:221], v[20:23]
	v_mfma_f32_16x16x32_bf16 v[6:9], v[186:189], v[226:229], v[8:11]
	v_mfma_f32_16x16x32_bf16 v[2:5], v[194:197], v[226:229], v[2:5]
	v_mfma_f32_16x16x32_bf16 v[56:59], v[190:193], v[206:209], v[56:59]
	v_mfma_f32_16x16x32_bf16 v[52:55], v[198:201], v[206:209], v[52:55]
	v_mfma_f32_16x16x32_bf16 v[40:43], v[190:193], v[214:217], v[40:43]
	v_mfma_f32_16x16x32_bf16 v[36:39], v[198:201], v[214:217], v[36:39]
	v_mfma_f32_16x16x32_bf16 v[24:27], v[190:193], v[222:225], v[24:27]
	v_mfma_f32_16x16x32_bf16 v[20:23], v[198:201], v[222:225], v[20:23]
	v_mfma_f32_16x16x32_bf16 v[8:11], v[190:193], v[230:233], v[6:9]
	v_mfma_f32_16x16x32_bf16 v[4:7], v[198:201], v[230:233], v[2:5]
	s_setprio 0
	s_barrier
	s_add_i32 s85, s85, 2
	s_add_u32 s83, s83, 0x100
	s_addc_u32 s84, s84, 0
	s_add_u32 s64, s64, 0x1080000
	s_addc_u32 s65, s65, 0
	s_cmp_gt_u32 s85, 29
	s_cbranch_scc1 .LBB0_392

;     __device__ __forceinline__ bool next(int i, Unit& u) const { if (i > 0) return false; u = u0; return true; }
; #define PG8_WAIT_V(n) asm volatile("s_waitcnt vmcnt(" #n ")" ::: "memory")
; template <class Epi, class Sched, bool ALIGN_EPI = false, bool SP2 = false>
; __device__ __forceinline__ void gemm_phase(PG8_LAS unsigned char* lds, const Gemm g, const Sched& S, const Epi& E) {
;     ...
;         PG8_WAIT_V(2); PG8_BAR;
;         PG8_STAGE(PG8_SB(1, 0), cB + kstep, voffB); PG8_STAGE(PG8_SA(1, 0), cA + kstep, voffA); PG8_STAGE(PG8_SB(1, 1), cB + hstep + kstep, voffB);
;         PG8_WAIT_V(6); PG8_BAR;
;     } else {
;         PG8_STAGE(PG8_SB(0, 0), cB, voffB); PG8_STAGE(PG8_SA(0, 0), cA, voffA); PG8_STAGE(PG8_SB(0, 1), cB + hstep, voffB); PG8_STAGE(PG8_SA(0, 1), cA + hstepA, voffA);
;         if (wr == 1) PG8_BAR;
;         PG8_WAIT_V(4); PG8_BAR;
;         PG8_STAGE(PG8_SB(1, 0), cB + kstep, voffB); PG8_STAGE(PG8_SA(1, 0), cA + kstep, voffA); PG8_STAGE(PG8_SB(1, 1), cB + hstep + kstep, voffB);
;         PG8_WAIT_V(6); PG8_BAR;
;     }
;     for (;;) {
;         const bool has_next = S.next(ui + 1, nxt);
;         const char* nA = has_next ? (const char*)g.A + (size_t)nxt.pm * tstepA : cA; const char* nB = has_next ? (const char*)g.Bt + (size_t)nxt.pn * tstep : cB;
;         for (int t = 0; t < nt; t += 2) {
;             if constexpr (Epi::MIDSCALE) { if (t == (nt >> 1)) E.midscale(acc, cur, wr, fr, ui); }
;             const bool last = (t == nt - 2);
;             const char* a1 = cA + (size_t)(t >> 1) * apair + kstep;
;             const char* a2 = last ? nA : cA + (size_t)((t >> 1) + 1) * apair; const char* b2 = last ? nB : cB + (size_t)(t + 2) * kstep;
;             const char* a3 = a2 + kstep; const char* b3 = b2 + kstep;
;             if (last && has_next) S.a_ready(nxt, ui + 1);
;             if constexpr (SP2) {
;             PG8_LDB(B0, 0, 0); PG8_LDB(B1, 0, 1); PG8_SCHED; PG8_LDA(At, 0, 0); PG8_STAGE(PG8_SA(1, 1), a1 + hstepA, voffA);
;             PG8_WAIT_V(8); PG8_WAIT_L(0); PG8_BAR; PG8_MMA(0, 0, At, B0); PG8_MMA(0, 1, At, B1); PG8_BAR; PG8_SCHED;
;             PG8_LDA(At, 0, 1); PG8_STAGE(PG8_SB(0, 0), b2, voffB); PG8_STAGE(PG8_SB(0, 1), b2 + hstep, voffB); PG8_STAGE(PG8_SA(0, 0), a2, voffA);
;             PG8_WAIT_V(8); PG8_WAIT_L(0); PG8_BAR; PG8_MMA(1, 0, At, B0); PG8_MMA(1, 1, At, B1); PG8_BAR; PG8_SCHED;
.LBB0_417:
	s_add_i32 s42, 0, 0x18000
	s_and_b32 s0, s0, 3
	s_add_i32 s30, s42, s12
	s_lshl_b32 s7, s0, 12
	s_lshl_b32 s13, s6, 13
	v_lshl_add_u64 v[18:19], v[2:3], 0, s[48:49]
	s_mov_b32 m0, s30
	s_add_i32 s46, s30, 0x2000
	s_add_i32 s35, s16, 0x8000
	s_add_i32 s47, s16, 0xa000
	s_waitcnt vmcnt(2)
	s_barrier
	global_load_lds_dwordx4 v[18:19], off
	v_lshl_add_u64 v[22:23], v[4:5], 0, s[48:49]
	s_mov_b32 m0, s46
	s_add_u32 s26, s4, 0x80080
	global_load_lds_dwordx4 v[22:23], off
	v_lshl_add_u64 v[16:17], v[20:21], 0, s[48:49]
	s_mov_b32 m0, s35
	s_addc_u32 s27, s5, 0
	s_add_i32 s43, 0, 0x1c000
	global_load_lds_dwordx4 v[16:17], off
	v_lshl_add_u64 v[24:25], v[28:29], 0, s[48:49]
	s_mov_b32 m0, s47
	s_add_i32 s50, s43, s12
	global_load_lds_dwordx4 v[24:25], off
	v_lshl_add_u64 v[30:31], s[26:27], 0, v[0:1]
	s_mov_b32 m0, s50
	s_add_i32 s51, s50, 0x2000
	global_load_lds_dwordx4 v[30:31], off
	v_lshl_add_u64 v[32:33], s[26:27], 0, v[34:35]
	s_mov_b32 m0, s51
	v_and_b32_e32 v6, 15, v36
	global_load_lds_dwordx4 v[32:33], off
	v_and_b32_e32 v134, 48, v36
	v_lshlrev_b32_e32 v7, 2, v36
	v_lshl_or_b32 v132, s6, 6, v6
	v_lshl_or_b32 v6, v6, 6, v134
	v_and_b32_e32 v7, 32, v7
	v_bitop3_b32 v36, v6, s7, v7 bitop3:0xde
	s_add_i32 s58, 0, 0x10000
	s_add_i32 s60, 0, 0x14000
	v_add_u32_e32 v135, s42, v36
	s_add_u32 s42, s20, 0x1080000
	v_add_u32_e32 v177, s43, v36
	s_addc_u32 s43, s21, 0
	s_add_u32 s6, s20, 0x1080080
	s_addc_u32 s7, s21, 0
	v_add_u32_e32 v128, s58, v36
	s_add_u32 s64, s20, 0x8080
	s_waitcnt vmcnt(6)
	s_barrier
	v_add_u32_e32 v129, s60, v36
	s_addc_u32 s65, s21, 0
	s_add_i32 s58, s58, s12
	ds_read_b128 v[36:39], v128
	ds_read_b128 v[40:43], v128 offset:1024
	ds_read_b128 v[44:47], v128 offset:2048
	ds_read_b128 v[48:51], v128 offset:3072
	ds_read_b128 v[52:55], v129
	ds_read_b128 v[56:59], v129 offset:1024
	ds_read_b128 v[60:63], v129 offset:2048
	ds_read_b128 v[64:67], v129 offset:3072
	s_add_i32 s63, s16, 0xc000
	s_add_i32 s62, s16, 0xe000
	s_add_i32 s53, s58, 0x2000
	s_add_u32 s44, s4, 0x80100
	s_addc_u32 s45, s5, 0
	s_add_i32 s60, s60, s12
	s_add_i32 s59, s60, 0x2000
	s_add_u32 s26, s20, 0x1088000
	s_addc_u32 s27, s21, 0
	s_add_u32 s12, s4, 0x80180
	v_bitop3_b32 v6, v6, s13, v7 bitop3:0xde
	s_addc_u32 s13, s5, 0
	s_add_u32 s4, s20, 0x1088080
	s_addc_u32 s5, s21, 0
	v_add_u32_e32 v133, 0, v6
	s_cmpk_gt_u32 s61, 0xff
	s_mov_b32 m0, s63
	v_lshl_add_u64 v[6:7], s[64:65], 0, v[8:9]
	ds_read_b128 v[68:71], v133
	ds_read_b128 v[72:75], v133 offset:1024
	ds_read_b128 v[76:79], v133 offset:2048
	ds_read_b128 v[80:83], v133 offset:3072
	ds_read_b128 v[84:87], v133 offset:4096
	ds_read_b128 v[88:91], v133 offset:5120
	ds_read_b128 v[92:95], v133 offset:6144
	ds_read_b128 v[96:99], v133 offset:7168
	global_load_lds_dwordx4 v[6:7], off
	v_lshl_add_u64 v[6:7], s[64:65], 0, v[26:27]
	s_mov_b32 m0, s62
	s_nop 0
	global_load_lds_dwordx4 v[6:7], off
	s_waitcnt vmcnt(8)
	s_waitcnt lgkmcnt(0)
	s_barrier
	s_setprio 1
	v_mfma_f32_16x16x32_bf16 v[100:103], v[36:39], v[68:71], 0
	v_mfma_f32_16x16x32_bf16 v[104:107], v[44:47], v[68:71], 0
	v_mfma_f32_16x16x32_bf16 v[108:111], v[36:39], v[76:79], 0
	v_mfma_f32_16x16x32_bf16 v[112:115], v[44:47], v[76:79], 0
	v_mfma_f32_16x16x32_bf16 v[116:119], v[36:39], v[84:87], 0
	v_mfma_f32_16x16x32_bf16 v[120:123], v[44:47], v[84:87], 0
	v_mfma_f32_16x16x32_bf16 v[124:127], v[36:39], v[92:95], 0
	v_mfma_f32_16x16x32_bf16 v[136:139], v[44:47], v[92:95], 0
	v_mfma_f32_16x16x32_bf16 v[100:103], v[40:43], v[72:75], v[100:103]
	v_mfma_f32_16x16x32_bf16 v[104:107], v[48:51], v[72:75], v[104:107]
	v_mfma_f32_16x16x32_bf16 v[108:111], v[40:43], v[80:83], v[108:111]
	v_mfma_f32_16x16x32_bf16 v[112:115], v[48:51], v[80:83], v[112:115]
	v_mfma_f32_16x16x32_bf16 v[116:119], v[40:43], v[88:91], v[116:119]
	v_mfma_f32_16x16x32_bf16 v[120:123], v[48:51], v[88:91], v[120:123]
	v_mfma_f32_16x16x32_bf16 v[124:127], v[40:43], v[96:99], v[124:127]
	v_mfma_f32_16x16x32_bf16 v[136:139], v[48:51], v[96:99], v[136:139]
	s_setprio 0
	s_setprio 1
	v_mfma_f32_16x16x32_bf16 v[140:143], v[52:55], v[68:71], 0
	v_mfma_f32_16x16x32_bf16 v[68:71], v[60:63], v[68:71], 0
	v_mfma_f32_16x16x32_bf16 v[140:143], v[56:59], v[72:75], v[140:143]
	v_mfma_f32_16x16x32_bf16 v[68:71], v[64:67], v[72:75], v[68:71]
	v_mfma_f32_16x16x32_bf16 v[72:75], v[52:55], v[76:79], 0
	v_mfma_f32_16x16x32_bf16 v[76:79], v[60:63], v[76:79], 0
	v_mfma_f32_16x16x32_bf16 v[72:75], v[56:59], v[80:83], v[72:75]
	v_mfma_f32_16x16x32_bf16 v[76:79], v[64:67], v[80:83], v[76:79]
	v_mfma_f32_16x16x32_bf16 v[80:83], v[52:55], v[84:87], 0
	v_mfma_f32_16x16x32_bf16 v[84:87], v[60:63], v[84:87], 0
	v_mfma_f32_16x16x32_bf16 v[80:83], v[56:59], v[88:91], v[80:83]
	v_mfma_f32_16x16x32_bf16 v[84:87], v[64:67], v[88:91], v[84:87]
	v_mfma_f32_16x16x32_bf16 v[88:91], v[52:55], v[92:95], 0
	v_mfma_f32_16x16x32_bf16 v[92:95], v[60:63], v[92:95], 0
	v_mfma_f32_16x16x32_bf16 v[88:91], v[56:59], v[96:99], v[88:91]
	v_mfma_f32_16x16x32_bf16 v[92:95], v[64:67], v[96:99], v[92:95]
	s_setprio 0
	s_barrier
	s_mov_b64 s[20:21], 0x100
	s_mov_b32 m0, s58
	v_lshl_add_u64 v[6:7], v[2:3], 0, s[20:21]
	ds_read_b128 v[96:99], v133 offset:16384
	ds_read_b128 v[144:147], v133 offset:17408
	ds_read_b128 v[154:157], v133 offset:18432
	ds_read_b128 v[158:161], v133 offset:19456
	ds_read_b128 v[162:165], v133 offset:20480
	ds_read_b128 v[178:181], v133 offset:21504
	ds_read_b128 v[182:185], v133 offset:22528
	ds_read_b128 v[186:189], v133 offset:23552
	global_load_lds_dwordx4 v[6:7], off
	v_lshl_add_u64 v[6:7], v[4:5], 0, s[20:21]
	s_mov_b32 m0, s53
	s_nop 0
	global_load_lds_dwordx4 v[6:7], off
	v_lshl_add_u64 v[6:7], s[44:45], 0, v[0:1]
	s_mov_b32 m0, s60
	s_nop 0
	global_load_lds_dwordx4 v[6:7], off
	v_lshl_add_u64 v[6:7], s[44:45], 0, v[34:35]
	s_mov_b32 m0, s59
	s_nop 0
	global_load_lds_dwordx4 v[6:7], off
	v_lshl_add_u64 v[6:7], s[42:43], 0, v[8:9]
	s_mov_b32 m0, s16
	s_nop 0
	global_load_lds_dwordx4 v[6:7], off
	v_lshl_add_u64 v[6:7], s[42:43], 0, v[26:27]
	s_mov_b32 m0, s52
	s_nop 0
	global_load_lds_dwordx4 v[6:7], off
	s_waitcnt vmcnt(8)
	s_waitcnt lgkmcnt(0)
	s_barrier
; #define PG8_STAGE(bufoff, gbase, voff) do { _Pragma("unroll") for (int _i = 0; _i < 2; ++_i) \
;         __builtin_amdgcn_global_load_lds((const unsigned*)((const char*)(gbase) + (voff)[_i]), (PG8_LAS unsigned*)(lds + (bufoff) + ldsw + _i * 8192), 16, 0, 0); } while (0)
; #define PG8_LDA(dst, b, h) do { _Pragma("unroll") for (int m = 0; m < 4; ++m) _Pragma("unroll") for (int k = 0; k < 2; ++k) dst[m][k] = *(const PG8_LAS bf16x8*)(lds + PG8_SA(b, h) + aoff + m * 2048 + k * 1024); } while (0)
; #define PG8_LDB(dst, b, h) do { _Pragma("unroll") for (int n = 0; n < 2; ++n) _Pragma("unroll") for (int k = 0; k < 2; ++k) dst[n][k] = *(const PG8_LAS bf16x8*)(lds + PG8_SB(b, h) + boff + n * 2048 + k * 1024); } while (0)
; #define PG8_MMA(ai, bj, At, Bt) do { __builtin_amdgcn_s_setprio(1); _Pragma("unroll") for (int m = 0; m < 4; ++m) _Pragma("unroll") for (int n = 0; n < 2; ++n) _Pragma("unroll") for (int k = 0; k < 2; ++k) \
;         acc[ai][bj][m][n] = __builtin_amdgcn_mfma_f32_16x16x32_bf16(Bt[n][k], At[m][k], acc[ai][bj][m][n], 0, 0, 0); __builtin_amdgcn_s_setprio(0); } while (0)
; #define PG8_WAIT_V(n) asm volatile("s_waitcnt vmcnt(" #n ")" ::: "memory")
; #define PG8_WAIT_L(n) asm volatile("s_waitcnt lgkmcnt(" #n ")" ::: "memory")
; #define PG8_BAR __builtin_amdgcn_s_barrier()
; #define PG8_SCHED __builtin_amdgcn_sched_barrier(0)
; template <class Epi, class Sched, bool ALIGN_EPI = false, bool SP2 = false>
; __device__ __forceinline__ void gemm_phase(PG8_LAS unsigned char* lds, const Gemm g, const Sched& S, const Epi& E) {
;     ...
;             PG8_WAIT_V(8); PG8_WAIT_L(0); PG8_BAR; PG8_MMA(1, 0, At, B0); PG8_MMA(1, 1, At, B1); PG8_BAR; PG8_SCHED;
;             PG8_LDB(B0, 1, 0); PG8_LDB(B1, 1, 1); PG8_SCHED; PG8_LDA(At, 1, 0); PG8_STAGE(PG8_SA(0, 1), a2 + hstepA, voffA);
;             PG8_WAIT_V(8); PG8_WAIT_L(0); PG8_BAR; PG8_MMA(0, 0, At, B0); PG8_MMA(0, 1, At, B1); PG8_BAR; PG8_SCHED;
	s_setprio 1
	v_mfma_f32_16x16x32_bf16 v[190:193], v[36:39], v[96:99], 0
	v_mfma_f32_16x16x32_bf16 v[198:201], v[36:39], v[154:157], 0
	v_mfma_f32_16x16x32_bf16 v[206:209], v[36:39], v[162:165], 0
	v_mfma_f32_16x16x32_bf16 v[36:39], v[36:39], v[182:185], 0
	v_mfma_f32_16x16x32_bf16 v[190:193], v[40:43], v[144:147], v[190:193]
	v_mfma_f32_16x16x32_bf16 v[198:201], v[40:43], v[158:161], v[198:201]
	v_mfma_f32_16x16x32_bf16 v[206:209], v[40:43], v[178:181], v[206:209]
	v_mfma_f32_16x16x32_bf16 v[36:39], v[40:43], v[186:189], v[36:39]
	v_mfma_f32_16x16x32_bf16 v[40:43], v[44:47], v[182:185], 0
	v_mfma_f32_16x16x32_bf16 v[194:197], v[44:47], v[96:99], 0
	v_mfma_f32_16x16x32_bf16 v[202:205], v[44:47], v[154:157], 0
	v_mfma_f32_16x16x32_bf16 v[210:213], v[44:47], v[162:165], 0
	v_mfma_f32_16x16x32_bf16 v[40:43], v[48:51], v[186:189], v[40:43]
	v_mfma_f32_16x16x32_bf16 v[194:197], v[48:51], v[144:147], v[194:197]
	v_mfma_f32_16x16x32_bf16 v[202:205], v[48:51], v[158:161], v[202:205]
	v_mfma_f32_16x16x32_bf16 v[210:213], v[48:51], v[178:181], v[210:213]
	s_setprio 0
	s_setprio 1
	v_mfma_f32_16x16x32_bf16 v[44:47], v[52:55], v[96:99], 0
	v_mfma_f32_16x16x32_bf16 v[48:51], v[60:63], v[96:99], 0
	v_mfma_f32_16x16x32_bf16 v[44:47], v[56:59], v[144:147], v[44:47]
	v_mfma_f32_16x16x32_bf16 v[48:51], v[64:67], v[144:147], v[48:51]
	v_mfma_f32_16x16x32_bf16 v[96:99], v[52:55], v[154:157], 0
	v_mfma_f32_16x16x32_bf16 v[144:147], v[60:63], v[154:157], 0
	v_mfma_f32_16x16x32_bf16 v[154:157], v[52:55], v[162:165], 0
	v_mfma_f32_16x16x32_bf16 v[52:55], v[52:55], v[182:185], 0
	v_mfma_f32_16x16x32_bf16 v[96:99], v[56:59], v[158:161], v[96:99]
	v_mfma_f32_16x16x32_bf16 v[154:157], v[56:59], v[178:181], v[154:157]
	v_mfma_f32_16x16x32_bf16 v[52:55], v[56:59], v[186:189], v[52:55]
	v_mfma_f32_16x16x32_bf16 v[56:59], v[60:63], v[182:185], 0
	v_mfma_f32_16x16x32_bf16 v[144:147], v[64:67], v[158:161], v[144:147]
	v_mfma_f32_16x16x32_bf16 v[158:161], v[60:63], v[162:165], 0
	v_mfma_f32_16x16x32_bf16 v[56:59], v[64:67], v[186:189], v[56:59]
	v_mfma_f32_16x16x32_bf16 v[158:161], v[64:67], v[178:181], v[158:161]
	s_setprio 0
	s_barrier
	ds_read_b128 v[60:63], v135
	ds_read_b128 v[64:67], v135 offset:1024
	ds_read_b128 v[162:165], v135 offset:2048
	ds_read_b128 v[178:181], v135 offset:3072
	ds_read_b128 v[182:185], v177
	ds_read_b128 v[186:189], v177 offset:1024
	ds_read_b128 v[214:217], v177 offset:2048
	ds_read_b128 v[218:221], v177 offset:3072
	s_mov_b32 m0, s17
	v_lshl_add_u64 v[6:7], s[26:27], 0, v[8:9]
	ds_read_b128 v[222:225], v133 offset:32768
	ds_read_b128 v[226:229], v133 offset:33792
	ds_read_b128 v[230:233], v133 offset:34816
	ds_read_b128 v[234:237], v133 offset:35840
	ds_read_b128 v[238:241], v133 offset:36864
	ds_read_b128 v[242:245], v133 offset:37888
	ds_read_b128 v[246:249], v133 offset:38912
	ds_read_b128 v[250:253], v133 offset:39936
	global_load_lds_dwordx4 v[6:7], off
	v_lshl_add_u64 v[6:7], s[26:27], 0, v[26:27]
	s_mov_b32 m0, s28
	s_nop 0
	global_load_lds_dwordx4 v[6:7], off
	s_waitcnt vmcnt(8)
	s_waitcnt lgkmcnt(0)
	s_barrier
	s_setprio 1
	v_mfma_f32_16x16x32_bf16 v[100:103], v[60:63], v[222:225], v[100:103]
	v_mfma_f32_16x16x32_bf16 v[104:107], v[162:165], v[222:225], v[104:107]
	v_mfma_f32_16x16x32_bf16 v[108:111], v[60:63], v[230:233], v[108:111]
	v_mfma_f32_16x16x32_bf16 v[112:115], v[162:165], v[230:233], v[112:115]
	v_mfma_f32_16x16x32_bf16 v[116:119], v[60:63], v[238:241], v[116:119]
	v_mfma_f32_16x16x32_bf16 v[120:123], v[162:165], v[238:241], v[120:123]
	v_mfma_f32_16x16x32_bf16 v[124:127], v[60:63], v[246:249], v[124:127]
	v_mfma_f32_16x16x32_bf16 v[136:139], v[162:165], v[246:249], v[136:139]
	v_mfma_f32_16x16x32_bf16 v[100:103], v[64:67], v[226:229], v[100:103]
	v_mfma_f32_16x16x32_bf16 v[104:107], v[178:181], v[226:229], v[104:107]
	v_mfma_f32_16x16x32_bf16 v[108:111], v[64:67], v[234:237], v[108:111]
	v_mfma_f32_16x16x32_bf16 v[112:115], v[178:181], v[234:237], v[112:115]
	v_mfma_f32_16x16x32_bf16 v[116:119], v[64:67], v[242:245], v[116:119]
	v_mfma_f32_16x16x32_bf16 v[120:123], v[178:181], v[242:245], v[120:123]
	v_mfma_f32_16x16x32_bf16 v[124:127], v[64:67], v[250:253], v[124:127]
	v_mfma_f32_16x16x32_bf16 v[136:139], v[178:181], v[250:253], v[136:139]
	s_setprio 0
	s_setprio 1
	v_mfma_f32_16x16x32_bf16 v[68:71], v[214:217], v[222:225], v[68:71]
	v_mfma_f32_16x16x32_bf16 v[80:83], v[182:185], v[238:241], v[80:83]
	v_mfma_f32_16x16x32_bf16 v[84:87], v[214:217], v[238:241], v[84:87]
	v_mfma_f32_16x16x32_bf16 v[88:91], v[182:185], v[246:249], v[88:91]
	v_mfma_f32_16x16x32_bf16 v[92:95], v[214:217], v[246:249], v[92:95]
	v_mfma_f32_16x16x32_bf16 v[140:143], v[182:185], v[222:225], v[140:143]
	v_mfma_f32_16x16x32_bf16 v[68:71], v[218:221], v[226:229], v[68:71]
	v_mfma_f32_16x16x32_bf16 v[72:75], v[182:185], v[230:233], v[72:75]
	v_mfma_f32_16x16x32_bf16 v[76:79], v[214:217], v[230:233], v[76:79]
	v_mfma_f32_16x16x32_bf16 v[80:83], v[186:189], v[242:245], v[80:83]
	v_mfma_f32_16x16x32_bf16 v[84:87], v[218:221], v[242:245], v[84:87]
	v_mfma_f32_16x16x32_bf16 v[88:91], v[186:189], v[250:253], v[88:91]
	v_mfma_f32_16x16x32_bf16 v[92:95], v[218:221], v[250:253], v[92:95]
	v_mfma_f32_16x16x32_bf16 v[140:143], v[186:189], v[226:229], v[140:143]
	v_mfma_f32_16x16x32_bf16 v[72:75], v[186:189], v[234:237], v[72:75]
	v_mfma_f32_16x16x32_bf16 v[76:79], v[218:221], v[234:237], v[76:79]
	s_setprio 0
	s_barrier
; #define PG8_STAGE(bufoff, gbase, voff) do { _Pragma("unroll") for (int _i = 0; _i < 2; ++_i) \
;         __builtin_amdgcn_global_load_lds((const unsigned*)((const char*)(gbase) + (voff)[_i]), (PG8_LAS unsigned*)(lds + (bufoff) + ldsw + _i * 8192), 16, 0, 0); } while (0)
; #define PG8_LDA(dst, b, h) do { _Pragma("unroll") for (int m = 0; m < 4; ++m) _Pragma("unroll") for (int k = 0; k < 2; ++k) dst[m][k] = *(const PG8_LAS bf16x8*)(lds + PG8_SA(b, h) + aoff + m * 2048 + k * 1024); } while (0)
; #define PG8_LDB(dst, b, h) do { _Pragma("unroll") for (int n = 0; n < 2; ++n) _Pragma("unroll") for (int k = 0; k < 2; ++k) dst[n][k] = *(const PG8_LAS bf16x8*)(lds + PG8_SB(b, h) + boff + n * 2048 + k * 1024); } while (0)
; #define PG8_MMA(ai, bj, At, Bt) do { __builtin_amdgcn_s_setprio(1); _Pragma("unroll") for (int m = 0; m < 4; ++m) _Pragma("unroll") for (int n = 0; n < 2; ++n) _Pragma("unroll") for (int k = 0; k < 2; ++k) \
;         acc[ai][bj][m][n] = __builtin_amdgcn_mfma_f32_16x16x32_bf16(Bt[n][k], At[m][k], acc[ai][bj][m][n], 0, 0, 0); __builtin_amdgcn_s_setprio(0); } while (0)
; #define PG8_WAIT_V(n) asm volatile("s_waitcnt vmcnt(" #n ")" ::: "memory")
; #define PG8_WAIT_L(n) asm volatile("s_waitcnt lgkmcnt(" #n ")" ::: "memory")
; #define PG8_BAR __builtin_amdgcn_s_barrier()
; #define PG8_SCHED __builtin_amdgcn_sched_barrier(0)
; template <class Epi, class Sched, bool ALIGN_EPI = false, bool SP2 = false>
; __device__ __forceinline__ void gemm_phase(PG8_LAS unsigned char* lds, const Gemm g, const Sched& S, const Epi& E) {
;     ...
;             PG8_LDB(B0, 0, 0); PG8_LDB(B1, 0, 1); PG8_SCHED; PG8_LDA(At, 0, 0); PG8_STAGE(PG8_SA(1, 1), a1 + hstepA, voffA);
;             PG8_WAIT_V(8); PG8_WAIT_L(0); PG8_BAR; PG8_MMA(0, 0, At, B0); PG8_MMA(0, 1, At, B1); PG8_BAR; PG8_SCHED;
;     ...
;             PG8_LDA(At, 1, 1); PG8_STAGE(PG8_SB(1, 0), b3, voffB); PG8_STAGE(PG8_SB(1, 1), b3 + hstep, voffB); PG8_STAGE(PG8_SA(1, 0), a3, voffA);
;             PG8_WAIT_V(8); PG8_WAIT_L(0); PG8_BAR; PG8_MMA(1, 0, At, B0); PG8_MMA(1, 1, At, B1); PG8_BAR; PG8_SCHED;
	s_mov_b64 s[20:21], 0x180
	s_mov_b32 m0, s30
	v_lshl_add_u64 v[6:7], v[2:3], 0, s[20:21]
	ds_read_b128 v[222:225], v133 offset:49152
	ds_read_b128 v[226:229], v133 offset:50176
	ds_read_b128 v[230:233], v133 offset:51200
	ds_read_b128 v[234:237], v133 offset:52224
	ds_read_b128 v[238:241], v133 offset:53248
	ds_read_b128 v[242:245], v133 offset:54272
	ds_read_b128 v[246:249], v133 offset:55296
	ds_read_b128 v[250:253], v133 offset:56320
	global_load_lds_dwordx4 v[6:7], off
	v_lshl_add_u64 v[6:7], v[4:5], 0, s[20:21]
	s_mov_b32 m0, s46
	s_nop 0
	global_load_lds_dwordx4 v[6:7], off
	v_lshl_add_u64 v[6:7], s[12:13], 0, v[0:1]
	s_mov_b32 m0, s50
	s_nop 0
	global_load_lds_dwordx4 v[6:7], off
	v_lshl_add_u64 v[6:7], s[12:13], 0, v[34:35]
	s_mov_b32 m0, s51
	s_nop 0
	global_load_lds_dwordx4 v[6:7], off
	v_lshl_add_u64 v[6:7], s[6:7], 0, v[8:9]
	s_mov_b32 m0, s35
	s_nop 0
	global_load_lds_dwordx4 v[6:7], off
	v_lshl_add_u64 v[6:7], s[6:7], 0, v[26:27]
	s_mov_b32 m0, s47
	s_nop 0
	global_load_lds_dwordx4 v[6:7], off
	s_waitcnt vmcnt(8)
	s_waitcnt lgkmcnt(0)
	s_barrier
	s_setprio 1
	v_mfma_f32_16x16x32_bf16 v[34:37], v[60:63], v[246:249], v[36:39]
	v_mfma_f32_16x16x32_bf16 v[38:41], v[162:165], v[246:249], v[40:43]
	v_mfma_f32_16x16x32_bf16 v[190:193], v[60:63], v[222:225], v[190:193]
	v_mfma_f32_16x16x32_bf16 v[194:197], v[162:165], v[222:225], v[194:197]
	v_mfma_f32_16x16x32_bf16 v[198:201], v[60:63], v[230:233], v[198:201]
	v_mfma_f32_16x16x32_bf16 v[202:205], v[162:165], v[230:233], v[202:205]
	v_mfma_f32_16x16x32_bf16 v[206:209], v[60:63], v[238:241], v[206:209]
	v_mfma_f32_16x16x32_bf16 v[210:213], v[162:165], v[238:241], v[210:213]
	v_mfma_f32_16x16x32_bf16 v[34:37], v[64:67], v[250:253], v[34:37]
	v_mfma_f32_16x16x32_bf16 v[38:41], v[178:181], v[250:253], v[38:41]
	v_mfma_f32_16x16x32_bf16 v[190:193], v[64:67], v[226:229], v[190:193]
	v_mfma_f32_16x16x32_bf16 v[194:197], v[178:181], v[226:229], v[194:197]
	v_mfma_f32_16x16x32_bf16 v[198:201], v[64:67], v[234:237], v[198:201]
	v_mfma_f32_16x16x32_bf16 v[202:205], v[178:181], v[234:237], v[202:205]
	v_mfma_f32_16x16x32_bf16 v[206:209], v[64:67], v[242:245], v[206:209]
	v_mfma_f32_16x16x32_bf16 v[210:213], v[178:181], v[242:245], v[210:213]
	s_setprio 0
	s_setprio 1
	v_mfma_f32_16x16x32_bf16 v[42:45], v[182:185], v[222:225], v[44:47]
	v_mfma_f32_16x16x32_bf16 v[46:49], v[214:217], v[222:225], v[48:51]
	v_mfma_f32_16x16x32_bf16 v[60:63], v[182:185], v[230:233], v[96:99]
	v_mfma_f32_16x16x32_bf16 v[64:67], v[214:217], v[230:233], v[144:147]
	v_mfma_f32_16x16x32_bf16 v[96:99], v[182:185], v[238:241], v[154:157]
	v_mfma_f32_16x16x32_bf16 v[50:53], v[182:185], v[246:249], v[52:55]
	v_mfma_f32_16x16x32_bf16 v[54:57], v[214:217], v[246:249], v[56:59]
	v_mfma_f32_16x16x32_bf16 v[42:45], v[186:189], v[226:229], v[42:45]
	v_mfma_f32_16x16x32_bf16 v[46:49], v[218:221], v[226:229], v[46:49]
	v_mfma_f32_16x16x32_bf16 v[60:63], v[186:189], v[234:237], v[60:63]
	v_mfma_f32_16x16x32_bf16 v[64:67], v[218:221], v[234:237], v[64:67]
	v_mfma_f32_16x16x32_bf16 v[96:99], v[186:189], v[242:245], v[96:99]
	v_mfma_f32_16x16x32_bf16 v[144:147], v[214:217], v[238:241], v[158:161]
	v_mfma_f32_16x16x32_bf16 v[50:53], v[186:189], v[250:253], v[50:53]
	v_mfma_f32_16x16x32_bf16 v[54:57], v[218:221], v[250:253], v[54:57]
	v_mfma_f32_16x16x32_bf16 v[144:147], v[218:221], v[242:245], v[144:147]
	s_setprio 0
	s_barrier
	ds_read_b128 v[154:157], v128
	ds_read_b128 v[158:161], v128 offset:1024
	ds_read_b128 v[162:165], v128 offset:2048
	ds_read_b128 v[178:181], v128 offset:3072
	ds_read_b128 v[182:185], v129
	ds_read_b128 v[186:189], v129 offset:1024
	ds_read_b128 v[214:217], v129 offset:2048
	ds_read_b128 v[218:221], v129 offset:3072
	s_mov_b32 m0, s63
	v_lshl_add_u64 v[6:7], s[4:5], 0, v[8:9]
	ds_read_b128 v[222:225], v133
	ds_read_b128 v[226:229], v133 offset:1024
	ds_read_b128 v[230:233], v133 offset:2048
	ds_read_b128 v[234:237], v133 offset:3072
	ds_read_b128 v[238:241], v133 offset:4096
	ds_read_b128 v[242:245], v133 offset:5120
	ds_read_b128 v[246:249], v133 offset:6144
	ds_read_b128 v[250:253], v133 offset:7168
	global_load_lds_dwordx4 v[6:7], off
	v_lshl_add_u64 v[6:7], s[4:5], 0, v[26:27]
	s_mov_b32 m0, s62
	s_nop 0
	global_load_lds_dwordx4 v[6:7], off
	s_waitcnt vmcnt(8)
	s_waitcnt lgkmcnt(0)
	s_barrier
	s_setprio 1
	v_mfma_f32_16x16x32_bf16 v[112:115], v[162:165], v[230:233], v[112:115]
	v_mfma_f32_16x16x32_bf16 v[170:173], v[178:181], v[234:237], v[112:115]
	v_mfma_f32_16x16x32_bf16 v[112:115], v[154:157], v[238:241], v[116:119]
	v_mfma_f32_16x16x32_bf16 v[148:151], v[158:161], v[242:245], v[112:115]
	v_mfma_f32_16x16x32_bf16 v[112:115], v[162:165], v[238:241], v[120:123]
	v_mfma_f32_16x16x32_bf16 v[128:131], v[178:181], v[242:245], v[112:115]
	v_mfma_f32_16x16x32_bf16 v[112:115], v[154:157], v[246:249], v[124:127]
	v_mfma_f32_16x16x32_bf16 v[100:103], v[154:157], v[222:225], v[100:103]
	v_mfma_f32_16x16x32_bf16 v[104:107], v[162:165], v[222:225], v[104:107]
	v_mfma_f32_16x16x32_bf16 v[108:111], v[154:157], v[230:233], v[108:111]
	v_mfma_f32_16x16x32_bf16 v[122:125], v[158:161], v[250:253], v[112:115]
	v_mfma_f32_16x16x32_bf16 v[112:115], v[162:165], v[246:249], v[136:139]
	v_mfma_f32_16x16x32_bf16 v[100:103], v[158:161], v[226:229], v[100:103]
	v_mfma_f32_16x16x32_bf16 v[104:107], v[178:181], v[226:229], v[104:107]
	v_mfma_f32_16x16x32_bf16 v[108:111], v[158:161], v[234:237], v[108:111]
	v_mfma_f32_16x16x32_bf16 v[136:139], v[178:181], v[250:253], v[112:115]
	s_setprio 0
	s_setprio 1
	v_mfma_f32_16x16x32_bf16 v[72:75], v[182:185], v[230:233], v[72:75]
	v_mfma_f32_16x16x32_bf16 v[112:115], v[182:185], v[222:225], v[140:143]
	v_mfma_f32_16x16x32_bf16 v[68:71], v[214:217], v[222:225], v[68:71]
	v_mfma_f32_16x16x32_bf16 v[222:225], v[186:189], v[234:237], v[72:75]
	v_mfma_f32_16x16x32_bf16 v[72:75], v[214:217], v[230:233], v[76:79]
	v_mfma_f32_16x16x32_bf16 v[140:143], v[186:189], v[226:229], v[112:115]
	v_mfma_f32_16x16x32_bf16 v[68:71], v[218:221], v[226:229], v[68:71]
	v_mfma_f32_16x16x32_bf16 v[226:229], v[218:221], v[234:237], v[72:75]
	v_mfma_f32_16x16x32_bf16 v[72:75], v[182:185], v[238:241], v[80:83]
	v_mfma_f32_16x16x32_bf16 v[230:233], v[186:189], v[242:245], v[72:75]
	v_mfma_f32_16x16x32_bf16 v[72:75], v[214:217], v[238:241], v[84:87]
	v_mfma_f32_16x16x32_bf16 v[234:237], v[218:221], v[242:245], v[72:75]
	v_mfma_f32_16x16x32_bf16 v[72:75], v[182:185], v[246:249], v[88:91]
	v_mfma_f32_16x16x32_bf16 v[238:241], v[186:189], v[250:253], v[72:75]
	v_mfma_f32_16x16x32_bf16 v[72:75], v[214:217], v[246:249], v[92:95]
	v_mfma_f32_16x16x32_bf16 v[242:245], v[218:221], v[250:253], v[72:75]
	s_setprio 0
	s_barrier
; #define PG8_STAGE(bufoff, gbase, voff) do { _Pragma("unroll") for (int _i = 0; _i < 2; ++_i) \
;         __builtin_amdgcn_global_load_lds((const unsigned*)((const char*)(gbase) + (voff)[_i]), (PG8_LAS unsigned*)(lds + (bufoff) + ldsw + _i * 8192), 16, 0, 0); } while (0)
; #define PG8_LDA(dst, b, h) do { _Pragma("unroll") for (int m = 0; m < 4; ++m) _Pragma("unroll") for (int k = 0; k < 2; ++k) dst[m][k] = *(const PG8_LAS bf16x8*)(lds + PG8_SA(b, h) + aoff + m * 2048 + k * 1024); } while (0)
; #define PG8_LDB(dst, b, h) do { _Pragma("unroll") for (int n = 0; n < 2; ++n) _Pragma("unroll") for (int k = 0; k < 2; ++k) dst[n][k] = *(const PG8_LAS bf16x8*)(lds + PG8_SB(b, h) + boff + n * 2048 + k * 1024); } while (0)
; #define PG8_MMA(ai, bj, At, Bt) do { __builtin_amdgcn_s_setprio(1); _Pragma("unroll") for (int m = 0; m < 4; ++m) _Pragma("unroll") for (int n = 0; n < 2; ++n) _Pragma("unroll") for (int k = 0; k < 2; ++k) \
;         acc[ai][bj][m][n] = __builtin_amdgcn_mfma_f32_16x16x32_bf16(Bt[n][k], At[m][k], acc[ai][bj][m][n], 0, 0, 0); __builtin_amdgcn_s_setprio(0); } while (0)
; #define PG8_WAIT_V(n) asm volatile("s_waitcnt vmcnt(" #n ")" ::: "memory")
; #define PG8_WAIT_L(n) asm volatile("s_waitcnt lgkmcnt(" #n ")" ::: "memory")
; #define PG8_BAR __builtin_amdgcn_s_barrier()
; #define PG8_SCHED __builtin_amdgcn_sched_barrier(0)
; template <class Epi, class Sched, bool ALIGN_EPI = false, bool SP2 = false>
; __device__ __forceinline__ void gemm_phase(PG8_LAS unsigned char* lds, const Gemm g, const Sched& S, const Epi& E) {
;     ...
;             PG8_LDA(At, 0, 1); PG8_STAGE(PG8_SB(0, 0), b2, voffB); PG8_STAGE(PG8_SB(0, 1), b2 + hstep, voffB); PG8_STAGE(PG8_SA(0, 0), a2, voffA);
;             PG8_WAIT_V(8); PG8_WAIT_L(0); PG8_BAR; PG8_MMA(1, 0, At, B0); PG8_MMA(1, 1, At, B1); PG8_BAR; PG8_SCHED;
;             PG8_LDB(B0, 1, 0); PG8_LDB(B1, 1, 1); PG8_SCHED; PG8_LDA(At, 1, 0); PG8_STAGE(PG8_SA(0, 1), a2 + hstepA, voffA);
	s_mov_b32 m0, s58
	s_nop 3
	ds_read_b128 v[72:75], v133 offset:16384
	ds_read_b128 v[76:79], v133 offset:17408
	ds_read_b128 v[80:83], v133 offset:18432
	ds_read_b128 v[84:87], v133 offset:19456
	ds_read_b128 v[88:91], v133 offset:20480
	ds_read_b128 v[92:95], v133 offset:21504
	ds_read_b128 v[112:115], v133 offset:22528
	ds_read_b128 v[116:119], v133 offset:23552
	global_load_lds_dwordx4 v[2:3], off
	s_mov_b32 m0, s53
	s_nop 0
	global_load_lds_dwordx4 v[4:5], off
	s_mov_b32 m0, s60
	s_nop 0
	global_load_lds_dwordx4 v[12:13], off
	s_mov_b32 m0, s59
	s_nop 0
	global_load_lds_dwordx4 v[14:15], off
	s_mov_b32 m0, s16
	s_nop 0
	global_load_lds_dwordx4 v[20:21], off
	s_mov_b32 m0, s52
	s_nop 0
	global_load_lds_dwordx4 v[28:29], off
	s_waitcnt vmcnt(8)
	s_waitcnt lgkmcnt(0)
	s_barrier
	s_setprio 1
	v_mfma_f32_16x16x32_bf16 v[2:5], v[154:157], v[72:75], v[190:193]
	v_mfma_f32_16x16x32_bf16 v[12:15], v[162:165], v[72:75], v[194:197]
	v_mfma_f32_16x16x32_bf16 v[26:29], v[154:157], v[80:83], v[198:201]
	v_mfma_f32_16x16x32_bf16 v[34:37], v[154:157], v[112:115], v[34:37]
	v_mfma_f32_16x16x32_bf16 v[38:41], v[162:165], v[112:115], v[38:41]
	v_mfma_f32_16x16x32_bf16 v[2:5], v[158:161], v[76:79], v[2:5]
	v_mfma_f32_16x16x32_bf16 v[12:15], v[178:181], v[76:79], v[12:15]
	v_mfma_f32_16x16x32_bf16 v[26:29], v[158:161], v[84:87], v[26:29]
	v_mfma_f32_16x16x32_bf16 v[190:193], v[162:165], v[80:83], v[202:205]
	v_mfma_f32_16x16x32_bf16 v[194:197], v[154:157], v[88:91], v[206:209]
	v_mfma_f32_16x16x32_bf16 v[198:201], v[162:165], v[88:91], v[210:213]
	v_mfma_f32_16x16x32_bf16 v[34:37], v[158:161], v[116:119], v[34:37]
	v_mfma_f32_16x16x32_bf16 v[38:41], v[178:181], v[116:119], v[38:41]
	v_mfma_f32_16x16x32_bf16 v[190:193], v[178:181], v[84:87], v[190:193]
	v_mfma_f32_16x16x32_bf16 v[194:197], v[158:161], v[92:95], v[194:197]
	v_mfma_f32_16x16x32_bf16 v[198:201], v[178:181], v[92:95], v[198:201]
	s_setprio 0
	s_setprio 1
	v_mfma_f32_16x16x32_bf16 v[42:45], v[182:185], v[72:75], v[42:45]
	v_mfma_f32_16x16x32_bf16 v[154:157], v[186:189], v[76:79], v[42:45]
	v_mfma_f32_16x16x32_bf16 v[42:45], v[214:217], v[72:75], v[46:49]
	v_mfma_f32_16x16x32_bf16 v[158:161], v[218:221], v[76:79], v[42:45]
	v_mfma_f32_16x16x32_bf16 v[42:45], v[182:185], v[80:83], v[60:63]
	v_mfma_f32_16x16x32_bf16 v[162:165], v[186:189], v[84:87], v[42:45]
	v_mfma_f32_16x16x32_bf16 v[42:45], v[214:217], v[80:83], v[64:67]
	v_mfma_f32_16x16x32_bf16 v[178:181], v[218:221], v[84:87], v[42:45]
	v_mfma_f32_16x16x32_bf16 v[42:45], v[182:185], v[88:91], v[96:99]
	v_mfma_f32_16x16x32_bf16 v[202:205], v[186:189], v[92:95], v[42:45]
	v_mfma_f32_16x16x32_bf16 v[42:45], v[214:217], v[88:91], v[144:147]
	v_mfma_f32_16x16x32_bf16 v[144:147], v[218:221], v[92:95], v[42:45]
	v_mfma_f32_16x16x32_bf16 v[42:45], v[182:185], v[112:115], v[50:53]
	v_mfma_f32_16x16x32_bf16 v[182:185], v[186:189], v[116:119], v[42:45]
	v_mfma_f32_16x16x32_bf16 v[42:45], v[214:217], v[112:115], v[54:57]
	v_mfma_f32_16x16x32_bf16 v[186:189], v[218:221], v[116:119], v[42:45]
	s_setprio 0
	s_barrier
	ds_read_b128 v[50:53], v135
	ds_read_b128 v[54:57], v135 offset:1024
	ds_read_b128 v[206:209], v135 offset:2048
	ds_read_b128 v[210:213], v135 offset:3072
	ds_read_b128 v[214:217], v177
	ds_read_b128 v[218:221], v177 offset:1024
	ds_read_b128 v[246:249], v177 offset:2048
	ds_read_b128 v[250:253], v177 offset:3072
	s_mov_b32 m0, s17
	ds_read_b128 v[42:45], v133 offset:32768
	ds_read_b128 v[46:49], v133 offset:33792
	ds_read_b128 v[58:61], v133 offset:34816
	ds_read_b128 v[62:65], v133 offset:35840
	ds_read_b128 v[94:97], v133 offset:36864
	ds_read_b128 v[6:9], v133 offset:37888
	ds_read_b128 v[72:75], v133 offset:38912
	ds_read_b128 v[76:79], v133 offset:39936
	global_load_lds_dwordx4 v[166:167], off
	s_mov_b32 m0, s28
	s_nop 0
	global_load_lds_dwordx4 v[10:11], off
	s_waitcnt vmcnt(8)
	s_waitcnt lgkmcnt(0)
	s_barrier
; #define PG8_STAGE(bufoff, gbase, voff) do { _Pragma("unroll") for (int _i = 0; _i < 2; ++_i) \
;         __builtin_amdgcn_global_load_lds((const unsigned*)((const char*)(gbase) + (voff)[_i]), (PG8_LAS unsigned*)(lds + (bufoff) + ldsw + _i * 8192), 16, 0, 0); } while (0)
; #define PG8_LDA(dst, b, h) do { _Pragma("unroll") for (int m = 0; m < 4; ++m) _Pragma("unroll") for (int k = 0; k < 2; ++k) dst[m][k] = *(const PG8_LAS bf16x8*)(lds + PG8_SA(b, h) + aoff + m * 2048 + k * 1024); } while (0)
; #define PG8_MMA(ai, bj, At, Bt) do { __builtin_amdgcn_s_setprio(1); _Pragma("unroll") for (int m = 0; m < 4; ++m) _Pragma("unroll") for (int n = 0; n < 2; ++n) _Pragma("unroll") for (int k = 0; k < 2; ++k) \
;         acc[ai][bj][m][n] = __builtin_amdgcn_mfma_f32_16x16x32_bf16(Bt[n][k], At[m][k], acc[ai][bj][m][n], 0, 0, 0); __builtin_amdgcn_s_setprio(0); } while (0)
; #define PG8_WAIT_V(n) asm volatile("s_waitcnt vmcnt(" #n ")" ::: "memory")
; #define PG8_WAIT_L(n) asm volatile("s_waitcnt lgkmcnt(" #n ")" ::: "memory")
; #define PG8_BAR __builtin_amdgcn_s_barrier()
; #define PG8_SCHED __builtin_amdgcn_sched_barrier(0)
; template <class Epi, class Sched, bool ALIGN_EPI = false, bool SP2 = false>
; __device__ __forceinline__ void gemm_phase(PG8_LAS unsigned char* lds, const Gemm g, const Sched& S, const Epi& E) {
;     ...
;             PG8_WAIT_V(8); PG8_WAIT_L(0); PG8_BAR; PG8_MMA(0, 0, At, B0); PG8_MMA(0, 1, At, B1); PG8_BAR; PG8_SCHED;
;             PG8_LDA(At, 1, 1); PG8_STAGE(PG8_SB(1, 0), b3, voffB); PG8_STAGE(PG8_SB(1, 1), b3 + hstep, voffB); PG8_STAGE(PG8_SA(1, 0), a3, voffA);
;             PG8_WAIT_V(8); PG8_WAIT_L(0); PG8_BAR; PG8_MMA(1, 0, At, B0); PG8_MMA(1, 1, At, B1); PG8_BAR; PG8_SCHED;
	s_setprio 1
	v_mfma_f32_16x16x32_bf16 v[80:83], v[50:53], v[42:45], v[100:103]
	v_mfma_f32_16x16x32_bf16 v[114:117], v[54:57], v[46:49], v[80:83]
	v_mfma_f32_16x16x32_bf16 v[80:83], v[206:209], v[42:45], v[104:107]
	v_mfma_f32_16x16x32_bf16 v[118:121], v[210:213], v[46:49], v[80:83]
	v_mfma_f32_16x16x32_bf16 v[80:83], v[50:53], v[58:61], v[108:111]
	v_mfma_f32_16x16x32_bf16 v[98:101], v[54:57], v[62:65], v[80:83]
	v_mfma_f32_16x16x32_bf16 v[80:83], v[206:209], v[58:61], v[170:173]
	v_mfma_f32_16x16x32_bf16 v[90:93], v[50:53], v[72:75], v[122:125]
	v_mfma_f32_16x16x32_bf16 v[102:105], v[210:213], v[62:65], v[80:83]
	v_mfma_f32_16x16x32_bf16 v[80:83], v[50:53], v[94:97], v[148:151]
	v_mfma_f32_16x16x32_bf16 v[86:89], v[206:209], v[94:97], v[128:131]
	v_mfma_f32_16x16x32_bf16 v[170:173], v[54:57], v[76:79], v[90:93]
	v_mfma_f32_16x16x32_bf16 v[90:93], v[206:209], v[72:75], v[136:139]
	v_mfma_f32_16x16x32_bf16 v[82:85], v[54:57], v[6:9], v[80:83]
	v_mfma_f32_16x16x32_bf16 v[86:89], v[210:213], v[6:9], v[86:89]
	v_mfma_f32_16x16x32_bf16 v[148:151], v[210:213], v[76:79], v[90:93]
	s_setprio 0
	s_setprio 1
	v_mfma_f32_16x16x32_bf16 v[90:93], v[214:217], v[42:45], v[140:143]
	v_mfma_f32_16x16x32_bf16 v[42:45], v[246:249], v[42:45], v[68:71]
	v_mfma_f32_16x16x32_bf16 v[126:129], v[250:253], v[46:49], v[42:45]
	v_mfma_f32_16x16x32_bf16 v[42:45], v[214:217], v[58:61], v[222:225]
	v_mfma_f32_16x16x32_bf16 v[106:109], v[218:221], v[62:65], v[42:45]
	v_mfma_f32_16x16x32_bf16 v[42:45], v[246:249], v[58:61], v[226:229]
	v_mfma_f32_16x16x32_bf16 v[110:113], v[250:253], v[62:65], v[42:45]
	v_mfma_f32_16x16x32_bf16 v[42:45], v[214:217], v[94:97], v[230:233]
	v_mfma_f32_16x16x32_bf16 v[122:125], v[218:221], v[46:49], v[90:93]
	v_mfma_f32_16x16x32_bf16 v[90:93], v[218:221], v[6:9], v[42:45]
	v_mfma_f32_16x16x32_bf16 v[42:45], v[246:249], v[94:97], v[234:237]
	v_mfma_f32_16x16x32_bf16 v[94:97], v[250:253], v[6:9], v[42:45]
	v_mfma_f32_16x16x32_bf16 v[6:9], v[214:217], v[72:75], v[238:241]
	v_mfma_f32_16x16x32_bf16 v[136:139], v[218:221], v[76:79], v[6:9]
	v_mfma_f32_16x16x32_bf16 v[6:9], v[246:249], v[72:75], v[242:245]
	v_mfma_f32_16x16x32_bf16 v[66:69], v[250:253], v[76:79], v[6:9]
	s_setprio 0
	s_barrier
	s_mov_b32 m0, s30
	s_nop 3
	ds_read_b128 v[6:9], v133 offset:49152
	ds_read_b128 v[70:73], v133 offset:50176
	ds_read_b128 v[74:77], v133 offset:51200
	ds_read_b128 v[78:81], v133 offset:52224
	ds_read_b128 v[140:143], v133 offset:53248
	ds_read_b128 v[222:225], v133 offset:54272
	ds_read_b128 v[226:229], v133 offset:55296
	ds_read_b128 v[230:233], v133 offset:56320
	global_load_lds_dwordx4 v[18:19], off
	s_mov_b32 m0, s46
	s_nop 0
	global_load_lds_dwordx4 v[22:23], off
	s_mov_b32 m0, s50
	s_nop 0
	global_load_lds_dwordx4 v[30:31], off
	s_mov_b32 m0, s51
	s_nop 0
	global_load_lds_dwordx4 v[32:33], off
	s_mov_b32 m0, s35
	s_nop 0
	global_load_lds_dwordx4 v[16:17], off
	s_mov_b32 m0, s47
	s_nop 0
	global_load_lds_dwordx4 v[24:25], off
	s_waitcnt vmcnt(8)
	s_waitcnt lgkmcnt(0)
	s_barrier
	s_setprio 1
	v_mfma_f32_16x16x32_bf16 v[2:5], v[50:53], v[6:9], v[2:5]
	v_mfma_f32_16x16x32_bf16 v[62:65], v[54:57], v[70:73], v[2:5]
	v_mfma_f32_16x16x32_bf16 v[2:5], v[206:209], v[6:9], v[12:15]
	v_mfma_f32_16x16x32_bf16 v[58:61], v[210:213], v[70:73], v[2:5]
	v_mfma_f32_16x16x32_bf16 v[2:5], v[50:53], v[74:77], v[26:29]
	v_mfma_f32_16x16x32_bf16 v[46:49], v[54:57], v[78:81], v[2:5]
	v_mfma_f32_16x16x32_bf16 v[2:5], v[206:209], v[74:77], v[190:193]
	v_mfma_f32_16x16x32_bf16 v[42:45], v[210:213], v[78:81], v[2:5]
	v_mfma_f32_16x16x32_bf16 v[2:5], v[50:53], v[140:143], v[194:197]
	v_mfma_f32_16x16x32_bf16 v[30:33], v[54:57], v[222:225], v[2:5]
	v_mfma_f32_16x16x32_bf16 v[2:5], v[206:209], v[140:143], v[198:201]
	v_mfma_f32_16x16x32_bf16 v[26:29], v[210:213], v[222:225], v[2:5]
	v_mfma_f32_16x16x32_bf16 v[2:5], v[50:53], v[226:229], v[34:37]
	v_mfma_f32_16x16x32_bf16 v[14:17], v[54:57], v[230:233], v[2:5]
	v_mfma_f32_16x16x32_bf16 v[2:5], v[206:209], v[226:229], v[38:41]
	v_mfma_f32_16x16x32_bf16 v[10:13], v[210:213], v[230:233], v[2:5]
	s_setprio 0
	s_setprio 1
	v_mfma_f32_16x16x32_bf16 v[2:5], v[214:217], v[6:9], v[154:157]
	v_mfma_f32_16x16x32_bf16 v[54:57], v[218:221], v[70:73], v[2:5]
	v_mfma_f32_16x16x32_bf16 v[2:5], v[246:249], v[6:9], v[158:161]
	v_mfma_f32_16x16x32_bf16 v[50:53], v[250:253], v[70:73], v[2:5]
	v_mfma_f32_16x16x32_bf16 v[2:5], v[214:217], v[74:77], v[162:165]
	v_mfma_f32_16x16x32_bf16 v[38:41], v[218:221], v[78:81], v[2:5]
	v_mfma_f32_16x16x32_bf16 v[2:5], v[246:249], v[74:77], v[178:181]
	v_mfma_f32_16x16x32_bf16 v[34:37], v[250:253], v[78:81], v[2:5]
	v_mfma_f32_16x16x32_bf16 v[2:5], v[214:217], v[140:143], v[202:205]
	v_mfma_f32_16x16x32_bf16 v[22:25], v[218:221], v[222:225], v[2:5]
	v_mfma_f32_16x16x32_bf16 v[2:5], v[246:249], v[140:143], v[144:147]
	v_mfma_f32_16x16x32_bf16 v[18:21], v[250:253], v[222:225], v[2:5]
	v_mfma_f32_16x16x32_bf16 v[2:5], v[214:217], v[226:229], v[182:185]
	v_mfma_f32_16x16x32_bf16 v[6:9], v[218:221], v[230:233], v[2:5]
	v_mfma_f32_16x16x32_bf16 v[2:5], v[246:249], v[226:229], v[186:189]
	v_mfma_f32_16x16x32_bf16 v[2:5], v[250:253], v[230:233], v[2:5]
	s_setprio 0
	s_barrier
	s_cbranch_scc1 .LBB0_419
	s_barrier
